# combination: ret_out instruction selection + ret_out K/V loads with the Q loads + barrier leader release before its invalidate
# speedup vs baseline: 1.0030x; 1.0030x over previous
.LBB0_193:
	v_mul_f32_e32 v0, 0xbfb8aa3b, v65
	v_rndne_f32_e32 v1, v0
	v_sub_f32_e32 v2, v0, v1
	v_fma_f32 v0, v65, s70, -v0
	v_fmac_f32_e32 v0, 0xb2a5705f, v65
	v_add_f32_e32 v0, v2, v0
	v_cvt_i32_f32_e32 v1, v1
	v_exp_f32_e32 v0, v0
	v_cmp_nlt_f32_e32 vcc, s71, v65
	s_ashr_i32 s39, s38, 31
	s_lshl_b64 s[26:27], s[38:39], 14
	v_ldexp_f32 v0, v0, v1
	v_cndmask_b32_e32 v0, 0, v0, vcc
	v_cmp_ngt_f32_e32 vcc, s3, v65
	s_add_u32 s26, s58, s26
	v_ashrrev_i32_e32 v86, 3, v100
	v_cndmask_b32_e32 v2, v238, v0, vcc
	v_add_f32_e32 v3, 1.0, v2
	v_add_f32_e32 v0, -1.0, v3
	v_sub_f32_e32 v1, v0, v3
	v_add_f32_e32 v1, 1.0, v1
	v_sub_f32_e32 v0, v2, v0
	v_add_f32_e32 v4, v0, v1
	v_frexp_mant_f32_e32 v0, v3
	v_cmp_gt_f32_e32 vcc, s5, v0
	v_cvt_f64_f32_e32 v[0:1], v3
	v_frexp_exp_i32_f64_e32 v0, v[0:1]
	v_subbrev_co_u32_e32 v0, vcc, 0, v0, vcc
	v_sub_u32_e32 v1, 0, v0
	v_ldexp_f32 v3, v3, v1
	v_ldexp_f32 v1, v4, v1
	v_add_f32_e32 v4, -1.0, v3
	v_add_f32_e32 v7, 1.0, v3
	v_add_f32_e32 v5, 1.0, v4
	v_add_f32_e32 v15, -1.0, v7
	v_sub_f32_e32 v5, v3, v5
	v_sub_f32_e32 v3, v3, v15
	v_add_f32_e32 v5, v1, v5
	v_add_f32_e32 v1, v1, v3
	v_add_f32_e32 v3, v7, v1
	v_rcp_f32_e32 v15, v3
	v_add_f32_e32 v6, v4, v5
	v_sub_f32_e32 v4, v4, v6
	v_add_f32_e32 v4, v5, v4
	v_sub_f32_e32 v5, v7, v3
	v_add_f32_e32 v1, v1, v5
	v_mul_f32_e32 v5, v6, v15
	v_mul_f32_e32 v7, v3, v5
	v_fma_f32 v17, v5, v3, -v7
	v_fmac_f32_e32 v17, v5, v1
	v_add_f32_e32 v18, v7, v17
	v_sub_f32_e32 v19, v6, v18
	v_sub_f32_e32 v6, v6, v19
	v_sub_f32_e32 v7, v18, v7
	v_sub_f32_e32 v6, v6, v18
	v_add_f32_e32 v4, v4, v6
	v_sub_f32_e32 v6, v7, v17
	v_add_f32_e32 v4, v6, v4
	v_add_f32_e32 v6, v19, v4
	v_mul_f32_e32 v7, v15, v6
	v_mul_f32_e32 v17, v3, v7
	v_fma_f32 v3, v7, v3, -v17
	v_fmac_f32_e32 v3, v7, v1
	v_sub_f32_e32 v1, v19, v6
	v_add_f32_e32 v1, v4, v1
	v_add_f32_e32 v4, v17, v3
	v_sub_f32_e32 v18, v6, v4
	v_sub_f32_e32 v6, v6, v18
	v_sub_f32_e32 v17, v4, v17
	v_sub_f32_e32 v4, v6, v4
	v_add_f32_e32 v1, v1, v4
	v_sub_f32_e32 v3, v17, v3
	v_cvt_f32_i32_e32 v0, v0
	v_add_f32_e32 v1, v3, v1
	v_add_f32_e32 v3, v5, v7
	v_add_f32_e32 v1, v18, v1
	v_sub_f32_e32 v4, v3, v5
	v_mul_f32_e32 v1, v15, v1
	v_sub_f32_e32 v4, v7, v4
	v_add_f32_e32 v1, v4, v1
	v_mul_f32_e32 v7, 0x3f317218, v0
	v_add_f32_e32 v4, v3, v1
	v_fma_f32 v15, v0, s6, -v7
	v_mul_f32_e32 v5, v4, v4
	v_fmac_f32_e32 v15, 0xb102e308, v0
	v_sub_f32_e32 v0, v4, v3
	v_fmamk_f32 v6, v5, 0x3e9b6dac, v222
	v_sub_f32_e32 v0, v1, v0
	v_add_f32_e32 v1, v7, v15
	v_fmaak_f32 v6, v5, v6, 0x3f2aaada
	v_sub_f32_e32 v3, v1, v7
	v_ldexp_f32 v7, v4, 1
	v_mul_f32_e32 v4, v4, v5
	v_mul_f32_e32 v4, v4, v6
	v_add_f32_e32 v5, v7, v4
	v_sub_f32_e32 v6, v5, v7
	v_ldexp_f32 v0, v0, 1
	v_sub_f32_e32 v4, v4, v6
	v_add_f32_e32 v0, v0, v4
	v_add_f32_e32 v4, v5, v0
	v_sub_f32_e32 v5, v4, v5
	v_sub_f32_e32 v0, v0, v5
	v_add_f32_e32 v5, v1, v4
	v_sub_f32_e32 v6, v5, v1
	v_sub_f32_e32 v7, v5, v6
	v_sub_f32_e32 v3, v15, v3
	v_sub_f32_e32 v1, v1, v7
	v_sub_f32_e32 v4, v4, v6
	v_add_f32_e32 v1, v4, v1
	v_add_f32_e32 v4, v3, v0
	v_sub_f32_e32 v6, v4, v3
	v_sub_f32_e32 v7, v4, v6
	v_sub_f32_e32 v3, v3, v7
	v_sub_f32_e32 v0, v0, v6
	v_add_f32_e32 v1, v4, v1
	v_add_f32_e32 v0, v0, v3
	v_add_f32_e32 v3, v5, v1
	v_sub_f32_e32 v4, v3, v5
	v_sub_f32_e32 v1, v1, v4
	v_add_f32_e32 v0, v0, v1
	v_mul_f32_e32 v1, 0xbfb8aa3b, v63
	v_add_f32_e32 v0, v3, v0
	v_rndne_f32_e32 v3, v1
	v_sub_f32_e32 v4, v1, v3
	v_fma_f32 v1, v63, s70, -v1
	v_fmac_f32_e32 v1, 0xb2a5705f, v63
	v_add_f32_e32 v1, v4, v1
	v_exp_f32_e32 v1, v1
	v_cvt_i32_f32_e32 v3, v3
	v_cmp_neq_f32_e32 vcc, s21, v2
	s_addc_u32 s27, s59, s27
	v_ashrrev_i32_e32 v87, 31, v86
	v_cndmask_b32_e32 v0, v238, v0, vcc
	v_cmp_lt_f32_e64 vcc, |v2|, s7
	v_cvt_pk_bf16_f32 v82, v48, v49
	v_cvt_pk_bf16_f32 v83, v46, v47
	v_cvt_pk_bf16_f32 v84, v44, v45
	v_cvt_pk_bf16_f32 v85, v42, v43
	v_cvt_pk_bf16_f32 v40, v40, v41
	s_nop 1
	v_cndmask_b32_e32 v99, v0, v2, vcc
	v_ldexp_f32 v0, v1, v3
	v_cmp_nlt_f32_e32 vcc, s71, v63
	v_cvt_pk_bf16_f32 v41, v38, v39
	v_cvt_pk_bf16_f32 v42, v36, v37
	v_cvt_pk_bf16_f32 v43, v34, v31
	v_and_b32_e32 v101, 15, v100
	v_and_b32_e32 v107, 48, v100
	v_cndmask_b32_e32 v0, 0, v0, vcc
	v_cmp_ngt_f32_e32 vcc, s3, v63
	v_add_u32_e32 v98, s2, v107
	v_or_b32_e32 v116, 64, v101
	v_cndmask_b32_e32 v0, v238, v0, vcc
	v_add_f32_e32 v4, 1.0, v0
	v_add_f32_e32 v1, -1.0, v4
	v_sub_f32_e32 v2, v1, v4
	v_add_f32_e32 v2, 1.0, v2
	v_sub_f32_e32 v1, v0, v1
	v_add_f32_e32 v5, v1, v2
	v_frexp_mant_f32_e32 v1, v4
	v_cvt_f64_f32_e32 v[2:3], v4
	v_cmp_gt_f32_e32 vcc, s5, v1
	v_frexp_exp_i32_f64_e32 v1, v[2:3]
	s_lshl_b32 s88, s22, 1
	v_subbrev_co_u32_e32 v1, vcc, 0, v1, vcc
	v_sub_u32_e32 v2, 0, v1
	v_ldexp_f32 v3, v4, v2
	v_add_f32_e32 v4, -1.0, v3
	v_add_f32_e32 v6, 1.0, v3
	v_ldexp_f32 v2, v5, v2
	v_add_f32_e32 v5, 1.0, v4
	v_add_f32_e32 v7, -1.0, v6
	v_sub_f32_e32 v5, v3, v5
	v_sub_f32_e32 v3, v3, v7
	v_add_f32_e32 v5, v2, v5
	v_add_f32_e32 v2, v2, v3
	v_add_f32_e32 v17, v6, v2
	v_rcp_f32_e32 v3, v17
	v_add_f32_e32 v15, v4, v5
	v_sub_f32_e32 v4, v4, v15
	v_add_f32_e32 v18, v5, v4
	v_sub_f32_e32 v4, v6, v17
	v_add_f32_e32 v19, v2, v4
	v_mul_f32_e32 v2, v15, v3
	v_mul_f32_e32 v33, v17, v2
	v_fma_f32 v35, v2, v17, -v33
	v_fmac_f32_e32 v35, v2, v19
	v_add_f32_e32 v50, v33, v35
	v_sub_f32_e32 v54, v15, v50
	v_sub_f32_e32 v15, v15, v54
	v_sub_f32_e32 v33, v50, v33
	v_sub_f32_e32 v15, v15, v50
	v_add_f32_e32 v15, v18, v15
	v_sub_f32_e32 v18, v33, v35
	v_add_f32_e32 v15, v18, v15
	v_add_f32_e32 v33, v54, v15
	v_mul_f32_e32 v35, v3, v33
	v_mul_f32_e32 v63, v17, v35
	v_sub_f32_e32 v65, v54, v33
	v_lshlrev_b32_e32 v12, 4, v100
	v_fma_f32 v17, v35, v17, -v63
	v_and_b32_e32 v184, 0x70, v12
	v_fmac_f32_e32 v17, v35, v19
	v_lshl_add_u64 v[12:13], s[26:27], 0, v[184:185]
	v_lshlrev_b64 v[18:19], 7, v[86:87]
	v_lshl_add_u64 v[18:19], v[12:13], 0, v[18:19]
	global_load_dwordx4 v[66:69], v[18:19], off
	v_add_u32_e32 v18, 0x100, v100
	v_ashrrev_i32_e32 v88, 3, v18
	v_ashrrev_i32_e32 v89, 31, v88
	v_lshlrev_b64 v[18:19], 7, v[88:89]
	v_lshl_add_u64 v[18:19], v[12:13], 0, v[18:19]
	global_load_dwordx4 v[70:73], v[18:19], off
	v_add_u32_e32 v18, 0x200, v100
	v_ashrrev_i32_e32 v90, 3, v18
	v_ashrrev_i32_e32 v91, 31, v90
	v_lshlrev_b64 v[18:19], 7, v[90:91]
	v_lshl_add_u64 v[18:19], v[12:13], 0, v[18:19]
	global_load_dwordx4 v[74:77], v[18:19], off
	v_add_u32_e32 v18, 0x300, v100
	v_ashrrev_i32_e32 v92, 3, v18
	v_ashrrev_i32_e32 v93, 31, v92
	v_lshlrev_b64 v[18:19], 7, v[92:93]
	v_lshl_add_u64 v[12:13], v[12:13], 0, v[18:19]
	global_load_dwordx4 v[78:81], v[12:13], off
	v_cvt_pk_bf16_f32 v19, v8, v9
	v_cvt_pk_bf16_f32 v8, v10, v11
	v_add_f32_e32 v13, v63, v17
	v_cvt_pk_bf16_f32 v9, v26, v27
	v_cvt_pk_bf16_f32 v10, v28, v29
	v_cvt_pk_bf16_f32 v11, v32, v30
	ds_write_b128 v16, v[8:11] offset:18480
	v_mul_u32_u24_e32 v8, 0x1100, v62
	v_add_f32_e32 v12, v15, v65
	v_sub_f32_e32 v15, v13, v63
	v_sub_f32_e32 v63, v33, v13
	v_mul_u32_u24_e32 v9, 0x21c0, v62
	v_lshlrev_b32_e32 v10, 1, v64
	v_lshlrev_b32_e32 v8, 1, v8
	v_sub_f32_e32 v18, v33, v63
	v_add3_u32 v9, v14, v9, v10
	v_add3_u32 v8, s2, v10, v8
	v_sub_f32_e32 v13, v18, v13
	ds_write_b128 v16, v[82:85] offset:18432
	ds_write_b128 v16, v[40:43] offset:18448
	v_cvt_pk_bf16_f32 v18, v20, v21
	v_cvt_pk_bf16_f32 v20, v22, v23
	v_cvt_pk_bf16_f32 v21, v24, v25
	ds_write_b128 v16, v[18:21] offset:18464
	v_and_b32_e32 v32, 0xffffffe0, v64
	v_or_b32_e32 v105, v32, v101
	v_add_f32_e32 v33, v12, v13
	v_mad_u64_u32 v[12:13], s[26:27], v105, s4, v[98:99]
	v_sub_f32_e32 v15, v15, v17
	v_cvt_f32_i32_e32 v1, v1
	v_cmp_neq_f32_e32 vcc, s21, v0
	v_or_b32_e32 v129, 16, v101
	v_or_b32_e32 v128, 32, v101
	v_mul_f32_e32 v39, 0x3f317218, v1
	v_fma_f32 v40, v1, s6, -v39
	v_fmac_f32_e32 v40, 0xb102e308, v1
	v_or_b32_e32 v127, 48, v101
	v_or_b32_e32 v119, 0x50, v101
	v_or_b32_e32 v117, 0x60, v101
	v_or_b32_e32 v115, 0x70, v101
	s_mov_b32 s36, 0x800000
	s_waitcnt vmcnt(0)
	ds_write_b16 v9, v194 offset:36864
	ds_write_b16_d16_hi v8, v194 offset:37136
	ds_write_b16 v9, v195 offset:37408
	ds_write_b16_d16_hi v9, v195 offset:37680
	ds_write_b16 v9, v196 offset:37952
	ds_write_b16_d16_hi v9, v196 offset:38224
	ds_write_b16 v9, v197 offset:38496
	ds_write_b16_d16_hi v9, v197 offset:38768
	ds_write_b16 v9, v198 offset:39040
	ds_write_b16_d16_hi v9, v198 offset:39312
	ds_write_b16 v9, v199 offset:39584
	ds_write_b16_d16_hi v9, v199 offset:39856
	ds_write_b16 v9, v200 offset:40128
	ds_write_b16_d16_hi v9, v200 offset:40400
	ds_write_b16 v9, v201 offset:40672
	ds_write_b16_d16_hi v9, v201 offset:40944
	ds_write_b16 v9, v206 offset:41216
	ds_write_b16_d16_hi v9, v206 offset:41488
	ds_write_b16 v9, v207 offset:41760
	ds_write_b16_d16_hi v9, v207 offset:42032
	ds_write_b16 v9, v208 offset:42304
	ds_write_b16_d16_hi v9, v208 offset:42576
	ds_write_b16 v9, v209 offset:42848
	ds_write_b16_d16_hi v9, v209 offset:43120
	ds_write_b16 v9, v202 offset:43392
	ds_write_b16_d16_hi v9, v202 offset:43664
	ds_write_b16 v9, v203 offset:43936
	ds_write_b16_d16_hi v9, v203 offset:44208
	ds_write_b16 v9, v204 offset:44480
	ds_write_b16_d16_hi v9, v204 offset:44752
	ds_write_b16 v9, v205 offset:45024
	ds_write_b16_d16_hi v9, v205 offset:45296
	v_add_u32_e32 v4, s2, v184
	v_mad_u64_u32 v[6:7], s[26:27], v86, s4, v[4:5]
	v_add_f32_e32 v8, v15, v33
	v_add_f32_e32 v8, v63, v8
	v_mul_f32_e32 v3, v3, v8
	v_add_f32_e32 v33, v2, v35
	ds_write_b128 v6, v[66:69] offset:54272
	v_mad_u64_u32 v[6:7], s[26:27], v88, s4, v[4:5]
	v_sub_f32_e32 v2, v33, v2
	v_sub_f32_e32 v2, v35, v2
	v_add_f32_e32 v35, v2, v3
	ds_write_b128 v6, v[70:73] offset:54272
	v_mad_u64_u32 v[6:7], s[26:27], v90, s4, v[4:5]
	v_mad_u64_u32 v[4:5], s[26:27], v92, s4, v[4:5]
	v_add_f32_e32 v36, v33, v35
	ds_write_b128 v6, v[74:77] offset:54272
	v_mul_f32_e32 v37, v36, v36
	v_fmamk_f32 v2, v37, 0x3e9b6dac, v222
	v_fmaak_f32 v38, v37, v2, 0x3f2aaada
	v_sub_f32_e32 v1, v36, v33
	v_add_f32_e32 v33, v39, v40
	ds_write_b128 v4, v[78:81] offset:54272
	v_mul_u32_u24_e32 v4, 0x48, v101
	v_lshlrev_b32_e32 v110, 1, v4
	v_add_u32_e32 v34, v98, v110
	s_waitcnt lgkmcnt(0)
	s_barrier
	ds_read_b128 v[24:27], v12
	ds_read_b128 v[28:31], v12 offset:2304
	ds_read_b128 v[4:7], v34 offset:18432
	ds_read_b128 v[20:23], v12 offset:64
	ds_read_b128 v[16:19], v12 offset:2368
	ds_read_b128 v[12:15], v34 offset:18496
	s_waitcnt lgkmcnt(3)
	v_mfma_f32_16x16x32_bf16 v[8:11], v[24:27], v[4:7], 0
	v_sub_f32_e32 v1, v35, v1
	v_ldexp_f32 v1, v1, 1
	v_add3_u32 v107, s2, v110, v107
	v_mfma_f32_16x16x32_bf16 v[4:7], v[28:31], v[4:7], 0
	v_add_u32_e32 v110, 0x1b00, v107
	s_waitcnt lgkmcnt(0)
	v_mfma_f32_16x16x32_bf16 v[92:95], v[20:23], v[12:15], v[8:11]
	s_nop 2
	ds_read_b128 v[8:11], v34 offset:20736
	v_mfma_f32_16x16x32_bf16 v[60:63], v[16:19], v[12:15], v[4:7]
	ds_read_b128 v[12:15], v34 offset:20800
	s_waitcnt lgkmcnt(1)
	v_mfma_f32_16x16x32_bf16 v[2:5], v[24:27], v[8:11], 0
	v_mfma_f32_16x16x32_bf16 v[6:9], v[28:31], v[8:11], 0
	v_sub_f32_e32 v10, v33, v39
	s_waitcnt lgkmcnt(0)
	v_mfma_f32_16x16x32_bf16 v[88:91], v[20:23], v[12:15], v[2:5]
	s_nop 3
	ds_read_b128 v[2:5], v34 offset:23040
	v_mfma_f32_16x16x32_bf16 v[56:59], v[16:19], v[12:15], v[6:9]
	v_sub_f32_e32 v14, v40, v10
	v_mul_f32_e32 v10, v36, v37
	v_mul_f32_e32 v35, v10, v38
	ds_read_b128 v[10:13], v34 offset:23104
	s_waitcnt lgkmcnt(1)
	v_mfma_f32_16x16x32_bf16 v[6:9], v[24:27], v[2:5], 0
	v_ldexp_f32 v15, v36, 1
	v_add_f32_e32 v36, v15, v35
	v_sub_f32_e32 v15, v36, v15
	v_mfma_f32_16x16x32_bf16 v[2:5], v[28:31], v[2:5], 0
	v_sub_f32_e32 v15, v35, v15
	v_add_f32_e32 v1, v1, v15
	v_add_f32_e32 v15, v36, v1
	s_waitcnt lgkmcnt(0)
	v_mfma_f32_16x16x32_bf16 v[84:87], v[20:23], v[10:13], v[6:9]
	v_add_f32_e32 v35, v33, v15
	s_nop 1
	ds_read_b128 v[6:9], v34 offset:25344
	v_mfma_f32_16x16x32_bf16 v[52:55], v[16:19], v[10:13], v[2:5]
	ds_read_b128 v[10:13], v34 offset:25408
	s_nop 1
	v_sub_f32_e32 v2, v15, v36
	v_sub_f32_e32 v1, v1, v2
	s_waitcnt lgkmcnt(1)
	v_mfma_f32_16x16x32_bf16 v[2:5], v[24:27], v[6:9], 0
	v_sub_f32_e32 v36, v35, v33
	v_sub_f32_e32 v37, v35, v36
	v_sub_f32_e32 v33, v33, v37
	v_mfma_f32_16x16x32_bf16 v[6:9], v[28:31], v[6:9], 0
	v_sub_f32_e32 v15, v15, v36
	v_add_f32_e32 v15, v15, v33
	v_mad_u32_u24 v33, v116, s4, v98
	s_waitcnt lgkmcnt(0)
	v_mfma_f32_16x16x32_bf16 v[80:83], v[20:23], v[10:13], v[2:5]
	v_add_f32_e32 v34, v14, v1
	v_lshlrev_b32_e32 v36, 5, v100
	v_and_b32_e32 v104, 32, v36
	ds_read_b128 v[2:5], v33 offset:18432
	v_mfma_f32_16x16x32_bf16 v[48:51], v[16:19], v[10:13], v[6:9]
	v_sub_f32_e32 v10, v34, v14
	v_sub_f32_e32 v11, v34, v10
	v_sub_f32_e32 v14, v14, v11
	v_sub_f32_e32 v1, v1, v10
	ds_read_b128 v[10:13], v33 offset:18496
	s_waitcnt lgkmcnt(1)
	v_mfma_f32_16x16x32_bf16 v[6:9], v[24:27], v[2:5], 0
	v_add_f32_e32 v1, v1, v14
	v_add_f32_e32 v14, v34, v15
	v_add_f32_e32 v15, v35, v14
	s_waitcnt lgkmcnt(0)
	v_mfma_f32_16x16x32_bf16 v[76:79], v[20:23], v[10:13], v[6:9]
	v_lshlrev_b32_e32 v184, 1, v104
	s_movk_i32 s4, 0x110
	s_nop 0
	v_sub_f32_e32 v6, v15, v35
	v_mfma_f32_16x16x32_bf16 v[2:5], v[28:31], v[2:5], 0
	v_sub_f32_e32 v14, v14, v6
	ds_read_b128 v[6:9], v33 offset:20736
	v_add_f32_e32 v1, v1, v14
	v_mfma_f32_16x16x32_bf16 v[44:47], v[16:19], v[10:13], v[2:5]
	ds_read_b128 v[10:13], v33 offset:20800
	v_add_f32_e32 v1, v15, v1
	v_cndmask_b32_e32 v1, v238, v1, vcc
	s_waitcnt lgkmcnt(1)
	v_mfma_f32_16x16x32_bf16 v[2:5], v[24:27], v[6:9], 0
	v_cmp_lt_f32_e64 vcc, |v0|, s7
	s_nop 1
	v_cndmask_b32_e32 v103, v1, v0, vcc
	v_lshrrev_b32_e32 v0, 1, v100
	v_mfma_f32_16x16x32_bf16 v[6:9], v[28:31], v[6:9], 0
	v_bfi_b32 v102, 31, v0, v64
	v_add_u32_e32 v96, s20, v102
	v_ashrrev_i32_e32 v97, 31, v96
	s_waitcnt lgkmcnt(0)
	v_mfma_f32_16x16x32_bf16 v[72:75], v[20:23], v[10:13], v[2:5]
	s_nop 2
	ds_read_b128 v[0:3], v33 offset:23040
	v_lshlrev_b64 v[4:5], 12, v[96:97]
	v_mfma_f32_16x16x32_bf16 v[40:43], v[16:19], v[10:13], v[6:9]
	s_nop 2
	v_lshl_add_u64 v[8:9], s[48:49], 0, v[4:5]
	v_lshl_add_u64 v[34:35], v[8:9], 0, s[88:89]
	ds_read_b128 v[8:11], v33 offset:23104
	s_waitcnt lgkmcnt(1)
	v_mfma_f32_16x16x32_bf16 v[4:7], v[24:27], v[0:3], 0
	v_lshl_add_u64 v[34:35], v[34:35], 0, v[184:185]
	v_mfma_f32_16x16x32_bf16 v[12:15], v[28:31], v[0:3], 0
	s_waitcnt lgkmcnt(0)
	v_mfma_f32_16x16x32_bf16 v[68:71], v[20:23], v[8:11], v[4:7]
	global_load_dwordx4 v[0:3], v[34:35], off offset:1584
	s_nop 2
	global_load_dwordx4 v[4:7], v[34:35], off offset:1568
	ds_read_b128 v[64:67], v33 offset:25344
	v_mfma_f32_16x16x32_bf16 v[36:39], v[16:19], v[8:11], v[12:15]
	global_load_dwordx4 v[8:11], v[34:35], off offset:1552
	s_nop 1
	global_load_dwordx4 v[12:15], v[34:35], off offset:1536
	ds_read_b128 v[130:133], v33 offset:25408
	v_lshrrev_b32_e32 v33, 2, v100
	v_and_or_b32 v100, v33, 12, v32
	v_sub_u32_e32 v32, v100, v101
	v_sub_u32_e32 v33, 0, v32
	v_max_i32_e32 v32, v32, v33
	v_cvt_f32_u32_e32 v106, v32
	s_waitcnt lgkmcnt(1)
	v_mfma_f32_16x16x32_bf16 v[120:123], v[24:27], v[64:67], 0
	v_cmp_lt_i32_e32 vcc, v100, v101
	v_or_b32_e32 v109, 1, v100
	s_waitcnt lgkmcnt(0)
	v_mfma_f32_16x16x32_bf16 v[134:137], v[28:31], v[64:67], 0
	v_cndmask_b32_e32 v108, v99, v103, vcc
	v_mul_f32_e32 v106, v108, v106
	v_mul_f32_e32 v106, 0xbfb8aa3b, v106
	v_mfma_f32_16x16x32_bf16 v[64:67], v[20:23], v[130:133], v[120:123]
	v_sad_u32 v108, v109, v101, 0
	v_mfma_f32_16x16x32_bf16 v[32:35], v[16:19], v[130:133], v[134:137]
	v_exp_f32_e32 v130, v106
	v_cvt_f32_u32_e32 v108, v108
	v_cmp_lt_i32_e32 vcc, v109, v101
	s_barrier
	v_mul_f32_e32 v92, v130, v92
	v_bfe_u32 v106, v92, 16, 1
	v_add3_u32 v106, v92, v106, s97
	v_mul_lo_u32 v92, v100, s4
	v_add_u32_e32 v113, s2, v92
	v_cndmask_b32_e32 v92, v99, v103, vcc
	v_mul_f32_e32 v92, v92, v108
	v_mul_f32_e32 v92, 0xbfb8aa3b, v92
	v_exp_f32_e32 v108, v92
	v_lshlrev_b32_e32 v92, 1, v101
	v_add_u32_e32 v118, v113, v92
	v_mul_f32_e32 v93, v108, v93
	v_or_b32_e32 v108, 2, v100
	v_sad_u32 v111, v108, v101, 0
	v_cvt_f32_u32_e32 v111, v111
	ds_write_b16_d16_hi v118, v106
	v_bfe_u32 v106, v93, 16, 1
	v_cmp_lt_i32_e32 vcc, v108, v101
	v_add3_u32 v106, v93, v106, s97
	v_add_u32_e32 v114, 0x110, v113
	v_cndmask_b32_e32 v93, v99, v103, vcc
	v_mul_f32_e32 v93, v93, v111
	v_mul_f32_e32 v93, 0xbfb8aa3b, v93
	v_exp_f32_e32 v111, v93
	v_add_u32_e32 v93, v114, v92
	ds_write_b16_d16_hi v93, v106
	v_or_b32_e32 v106, 3, v100
	v_sad_u32 v112, v106, v101, 0
	v_cvt_f32_u32_e32 v112, v112
	v_mul_f32_e32 v94, v111, v94
	v_cmp_lt_i32_e32 vcc, v106, v101
	v_cvt_pk_bf16_f32 v94, v94, v94
	v_or_b32_e32 v123, 16, v100
	v_cndmask_b32_e32 v111, v99, v103, vcc
	v_mul_f32_e32 v111, v111, v112
	v_mul_f32_e32 v111, 0xbfb8aa3b, v111
	v_exp_f32_e32 v111, v111
	v_add_u32_e32 v112, 0x220, v113
	v_add_u32_e32 v120, v112, v92
	ds_write_b16_d16_hi v120, v94
	v_mul_f32_e32 v94, v111, v95
	v_sad_u32 v111, v100, v129, 0
	v_cvt_f32_u32_e32 v111, v111
	v_bfe_u32 v95, v94, 16, 1
	v_cmp_lt_i32_e32 vcc, v100, v129
	v_add3_u32 v95, v94, v95, s97
	v_or_b32_e32 v122, 17, v100
	v_cndmask_b32_e32 v94, v99, v103, vcc
	v_mul_f32_e32 v94, v94, v111
	v_mul_f32_e32 v94, 0xbfb8aa3b, v94
	v_exp_f32_e32 v121, v94
	v_add_u32_e32 v111, 0x330, v113
	v_add_u32_e32 v94, v111, v92
	ds_write_b16_d16_hi v94, v95
	v_mul_f32_e32 v88, v121, v88
	v_cvt_pk_bf16_f32 v88, v88, v88
	v_sad_u32 v95, v109, v129, 0
	v_cvt_f32_u32_e32 v95, v95
	v_cmp_lt_i32_e32 vcc, v109, v129
	ds_write_b16_d16_hi v118, v88 offset:32
	v_mul_f32_e32 v56, v130, v56
	v_cndmask_b32_e32 v88, v99, v103, vcc
	v_mul_f32_e32 v88, v88, v95
	v_sad_u32 v95, v108, v129, 0
	v_mul_f32_e32 v88, 0xbfb8aa3b, v88
	v_exp_f32_e32 v88, v88
	v_cvt_f32_u32_e32 v95, v95
	v_cmp_lt_i32_e32 vcc, v108, v129
	v_mul_f32_e32 v88, v88, v89
	v_or_b32_e32 v121, 18, v100
	v_cndmask_b32_e32 v89, v99, v103, vcc
	v_mul_f32_e32 v89, v89, v95
	v_mul_f32_e32 v89, 0xbfb8aa3b, v89
	v_exp_f32_e32 v89, v89
	v_cvt_pk_bf16_f32 v88, v88, v88
	ds_write_b16_d16_hi v93, v88 offset:32
	v_mul_f32_e32 v88, v89, v90
	v_cvt_pk_bf16_f32 v88, v88, v88
	v_sad_u32 v89, v106, v129, 0
	v_cvt_f32_u32_e32 v89, v89
	v_cmp_lt_i32_e32 vcc, v106, v129
	ds_write_b16_d16_hi v120, v88 offset:32
	s_nop 0
	v_cndmask_b32_e32 v88, v99, v103, vcc
	v_mul_f32_e32 v88, v88, v89
	v_sad_u32 v89, v100, v128, 0
	v_cvt_f32_u32_e32 v89, v89
	v_cmp_lt_i32_e32 vcc, v100, v128
	v_mul_f32_e32 v88, 0xbfb8aa3b, v88
	v_exp_f32_e32 v88, v88
	v_cndmask_b32_e32 v90, v99, v103, vcc
	v_mul_f32_e32 v89, v90, v89
	v_mul_f32_e32 v89, 0xbfb8aa3b, v89
	v_exp_f32_e32 v89, v89
	v_mul_f32_e32 v88, v88, v91
	v_cvt_pk_bf16_f32 v88, v88, v88
	v_mul_f32_e32 v84, v89, v84
	ds_write_b16_d16_hi v94, v88 offset:32
	v_cvt_pk_bf16_f32 v84, v84, v84
	v_sad_u32 v88, v109, v128, 0
	v_cvt_f32_u32_e32 v88, v88
	v_cmp_lt_i32_e32 vcc, v109, v128
	ds_write_b16_d16_hi v118, v84 offset:64
	s_nop 0
	v_cndmask_b32_e32 v84, v99, v103, vcc
	v_mul_f32_e32 v84, v84, v88
	v_sad_u32 v88, v108, v128, 0
	v_mul_f32_e32 v84, 0xbfb8aa3b, v84
	v_exp_f32_e32 v84, v84
	v_cvt_f32_u32_e32 v88, v88
	v_cmp_lt_i32_e32 vcc, v108, v128
	v_mul_f32_e32 v84, v84, v85
	s_nop 0
	v_cndmask_b32_e32 v85, v99, v103, vcc
	v_mul_f32_e32 v85, v85, v88
	v_mul_f32_e32 v85, 0xbfb8aa3b, v85
	v_exp_f32_e32 v85, v85
	v_cvt_pk_bf16_f32 v84, v84, v84
	ds_write_b16_d16_hi v93, v84 offset:64
	v_mul_f32_e32 v84, v85, v86
	v_cvt_pk_bf16_f32 v84, v84, v84
	v_sad_u32 v85, v106, v128, 0
	v_cvt_f32_u32_e32 v85, v85
	v_cmp_lt_i32_e32 vcc, v106, v128
	ds_write_b16_d16_hi v120, v84 offset:64
	v_add_u32_e32 v88, 0x1200, v107
	v_cndmask_b32_e32 v84, v99, v103, vcc
	v_mul_f32_e32 v84, v84, v85
	v_sad_u32 v85, v100, v127, 0
	v_cvt_f32_u32_e32 v85, v85
	v_cmp_lt_i32_e32 vcc, v100, v127
	v_mul_f32_e32 v84, 0xbfb8aa3b, v84
	v_exp_f32_e32 v84, v84
	v_cndmask_b32_e32 v86, v99, v103, vcc
	v_mul_f32_e32 v85, v86, v85
	v_mul_f32_e32 v85, 0xbfb8aa3b, v85
	v_exp_f32_e32 v85, v85
	v_mul_f32_e32 v84, v84, v87
	v_cvt_pk_bf16_f32 v84, v84, v84
	v_mul_f32_e32 v80, v85, v80
	ds_write_b16_d16_hi v94, v84 offset:64
	v_cvt_pk_bf16_f32 v80, v80, v80
	v_sad_u32 v84, v109, v127, 0
	v_cvt_f32_u32_e32 v84, v84
	v_cmp_lt_i32_e32 vcc, v109, v127
	ds_write_b16_d16_hi v118, v80 offset:96
	s_nop 0
	v_cndmask_b32_e32 v80, v99, v103, vcc
	v_mul_f32_e32 v80, v80, v84
	v_sad_u32 v84, v108, v127, 0
	v_mul_f32_e32 v80, 0xbfb8aa3b, v80
	v_exp_f32_e32 v80, v80
	v_cvt_f32_u32_e32 v84, v84
	v_cmp_lt_i32_e32 vcc, v108, v127
	v_mul_f32_e32 v80, v80, v81
	s_nop 0
	v_cndmask_b32_e32 v81, v99, v103, vcc
	v_mul_f32_e32 v81, v81, v84
	v_mul_f32_e32 v81, 0xbfb8aa3b, v81
	v_exp_f32_e32 v81, v81
	v_cvt_pk_bf16_f32 v80, v80, v80
	ds_write_b16_d16_hi v93, v80 offset:96
	v_mul_f32_e32 v80, v81, v82
	v_cvt_pk_bf16_f32 v80, v80, v80
	v_sad_u32 v81, v106, v127, 0
	v_cvt_f32_u32_e32 v81, v81
	v_cmp_lt_i32_e32 vcc, v106, v127
	ds_write_b16_d16_hi v120, v80 offset:96
	s_nop 0
	v_cndmask_b32_e32 v80, v99, v103, vcc
	v_mul_f32_e32 v80, v80, v81
	v_sad_u32 v81, v100, v116, 0
	v_cvt_f32_u32_e32 v81, v81
	v_cmp_lt_i32_e32 vcc, v100, v116
	v_mul_f32_e32 v80, 0xbfb8aa3b, v80
	v_exp_f32_e32 v80, v80
	v_cndmask_b32_e32 v82, v99, v103, vcc
	v_mul_f32_e32 v81, v82, v81
	v_mul_f32_e32 v81, 0xbfb8aa3b, v81
	v_exp_f32_e32 v81, v81
	v_mul_f32_e32 v80, v80, v83
	v_cvt_pk_bf16_f32 v80, v80, v80
	v_mul_f32_e32 v76, v81, v76
	ds_write_b16_d16_hi v94, v80 offset:96
	v_cvt_pk_bf16_f32 v76, v76, v76
	v_sad_u32 v80, v109, v116, 0
	v_cvt_f32_u32_e32 v80, v80
	v_cmp_lt_i32_e32 vcc, v109, v116
	ds_write_b16_d16_hi v118, v76 offset:128
	s_nop 0
	v_cndmask_b32_e32 v76, v99, v103, vcc
	v_mul_f32_e32 v76, v76, v80
	v_sad_u32 v80, v108, v116, 0
	v_mul_f32_e32 v76, 0xbfb8aa3b, v76
	v_exp_f32_e32 v76, v76
	v_cvt_f32_u32_e32 v80, v80
	v_cmp_lt_i32_e32 vcc, v108, v116
	v_mul_f32_e32 v76, v76, v77
	s_nop 0
	v_cndmask_b32_e32 v77, v99, v103, vcc
	v_mul_f32_e32 v77, v77, v80
	v_mul_f32_e32 v77, 0xbfb8aa3b, v77
	v_exp_f32_e32 v77, v77
	v_cvt_pk_bf16_f32 v76, v76, v76
	ds_write_b16_d16_hi v93, v76 offset:128
	v_mul_f32_e32 v76, v77, v78
	v_cvt_pk_bf16_f32 v76, v76, v76
	v_sad_u32 v77, v106, v116, 0
	v_cvt_f32_u32_e32 v77, v77
	v_cmp_lt_i32_e32 vcc, v106, v116
	ds_write_b16_d16_hi v120, v76 offset:128
	s_nop 0
	v_cndmask_b32_e32 v76, v99, v103, vcc
	v_mul_f32_e32 v76, v76, v77
	v_sad_u32 v77, v100, v119, 0
	v_cvt_f32_u32_e32 v77, v77
	v_cmp_lt_i32_e32 vcc, v100, v119
	v_mul_f32_e32 v76, 0xbfb8aa3b, v76
	v_exp_f32_e32 v76, v76
	v_cndmask_b32_e32 v78, v99, v103, vcc
	v_mul_f32_e32 v77, v78, v77
	v_mul_f32_e32 v77, 0xbfb8aa3b, v77
	v_exp_f32_e32 v77, v77
	v_mul_f32_e32 v76, v76, v79
	v_cvt_pk_bf16_f32 v76, v76, v76
	v_mul_f32_e32 v72, v77, v72
	ds_write_b16_d16_hi v94, v76 offset:128
	v_cvt_pk_bf16_f32 v72, v72, v72
	v_sad_u32 v76, v109, v119, 0
	v_cvt_f32_u32_e32 v76, v76
	v_cmp_lt_i32_e32 vcc, v109, v119
	ds_write_b16_d16_hi v118, v72 offset:160
	s_nop 0
	v_cndmask_b32_e32 v72, v99, v103, vcc
	v_mul_f32_e32 v72, v72, v76
	v_sad_u32 v76, v108, v119, 0
	v_mul_f32_e32 v72, 0xbfb8aa3b, v72
	v_exp_f32_e32 v72, v72
	v_cvt_f32_u32_e32 v76, v76
	v_cmp_lt_i32_e32 vcc, v108, v119
	v_mul_f32_e32 v72, v72, v73
	s_nop 0
	v_cndmask_b32_e32 v73, v99, v103, vcc
	v_mul_f32_e32 v73, v73, v76
	v_mul_f32_e32 v73, 0xbfb8aa3b, v73
	v_exp_f32_e32 v73, v73
	v_cvt_pk_bf16_f32 v72, v72, v72
	ds_write_b16_d16_hi v93, v72 offset:160
	v_mul_f32_e32 v72, v73, v74
	v_cvt_pk_bf16_f32 v72, v72, v72
	v_sad_u32 v73, v106, v119, 0
	v_cvt_f32_u32_e32 v73, v73
	v_cmp_lt_i32_e32 vcc, v106, v119
	ds_write_b16_d16_hi v120, v72 offset:160
	s_nop 0
	v_cndmask_b32_e32 v72, v99, v103, vcc
	v_mul_f32_e32 v72, v72, v73
	v_sad_u32 v73, v100, v117, 0
	v_cvt_f32_u32_e32 v73, v73
	v_cmp_lt_i32_e32 vcc, v100, v117
	v_mul_f32_e32 v72, 0xbfb8aa3b, v72
	v_exp_f32_e32 v72, v72
	v_cndmask_b32_e32 v74, v99, v103, vcc
	v_mul_f32_e32 v73, v74, v73
	v_mul_f32_e32 v73, 0xbfb8aa3b, v73
	v_exp_f32_e32 v73, v73
	v_mul_f32_e32 v72, v72, v75
	v_cvt_pk_bf16_f32 v72, v72, v72
	v_mul_f32_e32 v68, v73, v68
	ds_write_b16_d16_hi v94, v72 offset:160
	v_cvt_pk_bf16_f32 v68, v68, v68
	v_sad_u32 v72, v109, v117, 0
	v_cvt_f32_u32_e32 v72, v72
	v_cmp_lt_i32_e32 vcc, v109, v117
	ds_write_b16_d16_hi v118, v68 offset:192
	s_nop 0
	v_cndmask_b32_e32 v68, v99, v103, vcc
	v_mul_f32_e32 v68, v68, v72
	v_sad_u32 v72, v108, v117, 0
	v_mul_f32_e32 v68, 0xbfb8aa3b, v68
	v_exp_f32_e32 v68, v68
	v_cvt_f32_u32_e32 v72, v72
	v_cmp_lt_i32_e32 vcc, v108, v117
	v_mul_f32_e32 v68, v68, v69
	s_nop 0
	v_cndmask_b32_e32 v69, v99, v103, vcc
	v_mul_f32_e32 v69, v69, v72
	v_mul_f32_e32 v69, 0xbfb8aa3b, v69
	v_exp_f32_e32 v69, v69
	v_cvt_pk_bf16_f32 v68, v68, v68
	ds_write_b16_d16_hi v93, v68 offset:192
	v_mul_f32_e32 v68, v69, v70
	v_cvt_pk_bf16_f32 v68, v68, v68
	v_sad_u32 v69, v106, v117, 0
	v_cvt_f32_u32_e32 v69, v69
	v_cmp_lt_i32_e32 vcc, v106, v117
	ds_write_b16_d16_hi v120, v68 offset:192
	s_nop 0
	v_cndmask_b32_e32 v68, v99, v103, vcc
	v_mul_f32_e32 v68, v68, v69
	v_sad_u32 v69, v100, v115, 0
	v_cvt_f32_u32_e32 v69, v69
	v_cmp_lt_i32_e32 vcc, v100, v115
	v_mul_f32_e32 v68, 0xbfb8aa3b, v68
	v_exp_f32_e32 v68, v68
	v_cndmask_b32_e32 v70, v99, v103, vcc
	v_mul_f32_e32 v69, v70, v69
	v_mul_f32_e32 v69, 0xbfb8aa3b, v69
	v_exp_f32_e32 v69, v69
	v_mul_f32_e32 v68, v68, v71
	v_cvt_pk_bf16_f32 v68, v68, v68
	v_mul_f32_e32 v64, v69, v64
	ds_write_b16_d16_hi v94, v68 offset:192
	v_cvt_pk_bf16_f32 v64, v64, v64
	v_sad_u32 v68, v109, v115, 0
	v_cvt_f32_u32_e32 v68, v68
	v_cmp_lt_i32_e32 vcc, v109, v115
	ds_write_b16_d16_hi v118, v64 offset:224
	v_or_b32_e32 v118, 19, v100
	v_cndmask_b32_e32 v64, v99, v103, vcc
	v_mul_f32_e32 v64, v64, v68
	v_sad_u32 v68, v108, v115, 0
	v_mul_f32_e32 v64, 0xbfb8aa3b, v64
	v_exp_f32_e32 v64, v64
	v_cvt_f32_u32_e32 v68, v68
	v_cmp_lt_i32_e32 vcc, v108, v115
	v_mul_f32_e32 v64, v64, v65
	s_nop 0
	v_cndmask_b32_e32 v65, v99, v103, vcc
	v_mul_f32_e32 v65, v65, v68
	v_mul_f32_e32 v65, 0xbfb8aa3b, v65
	v_exp_f32_e32 v65, v65
	v_cvt_pk_bf16_f32 v64, v64, v64
	ds_write_b16_d16_hi v93, v64 offset:224
	v_mul_f32_e32 v64, v65, v66
	v_cvt_pk_bf16_f32 v64, v64, v64
	v_sad_u32 v65, v106, v115, 0
	v_cvt_f32_u32_e32 v65, v65
	v_cmp_lt_i32_e32 vcc, v106, v115
	ds_write_b16_d16_hi v120, v64 offset:224
	v_add_u32_e32 v68, 0x900, v107
	v_cndmask_b32_e32 v64, v99, v103, vcc
	v_mul_f32_e32 v64, v64, v65
	v_sad_u32 v65, v123, v101, 0
	v_cvt_f32_u32_e32 v65, v65
	v_cmp_lt_i32_e32 vcc, v123, v101
	v_mul_f32_e32 v64, 0xbfb8aa3b, v64
	v_exp_f32_e32 v64, v64
	v_cndmask_b32_e32 v66, v99, v103, vcc
	v_mul_f32_e32 v65, v66, v65
	v_mul_f32_e32 v65, 0xbfb8aa3b, v65
	v_exp_f32_e32 v65, v65
	v_mul_f32_e32 v64, v64, v67
	v_cvt_pk_bf16_f32 v64, v64, v64
	v_mul_f32_e32 v60, v65, v60
	ds_write_b16_d16_hi v94, v64 offset:224
	v_bfe_u32 v64, v60, 16, 1
	v_add3_u32 v64, v60, v64, s97
	v_sad_u32 v60, v122, v101, 0
	v_cvt_f32_u32_e32 v60, v60
	v_cmp_lt_i32_e32 vcc, v122, v101
	v_mul_lo_u32 v65, v123, s4
	v_add_u32_e32 v126, s2, v65
	v_cndmask_b32_e32 v66, v99, v103, vcc
	v_mul_f32_e32 v60, v66, v60
	v_mul_f32_e32 v60, 0xbfb8aa3b, v60
	v_exp_f32_e32 v66, v60
	v_sub_u32_e32 v65, v121, v101
	v_add_u32_e32 v60, v126, v92
	ds_write_b16_d16_hi v60, v64
	v_mul_f32_e32 v61, v66, v61
	v_sub_u32_e32 v66, 0, v65
	v_max_i32_e32 v65, v65, v66
	v_cvt_f32_u32_e32 v65, v65
	v_cmp_lt_i32_e32 vcc, v121, v101
	v_cvt_pk_bf16_f32 v61, v61, v61
	v_add_u32_e32 v125, 0x110, v126
	v_cndmask_b32_e32 v64, v99, v103, vcc
	v_mul_f32_e32 v64, v64, v65
	v_mul_f32_e32 v64, 0xbfb8aa3b, v64
	v_exp_f32_e32 v65, v64
	v_add_u32_e32 v64, v125, v92
	ds_write_b16_d16_hi v64, v61
	v_cmp_lt_i32_e32 vcc, v118, v101
	v_mul_f32_e32 v61, v65, v62
	v_sad_u32 v65, v118, v101, 0
	v_cvt_f32_u32_e32 v65, v65
	v_bfe_u32 v62, v61, 16, 1
	v_add3_u32 v62, v61, v62, s97
	v_cndmask_b32_e32 v61, v99, v103, vcc
	v_mul_f32_e32 v61, v61, v65
	v_mul_f32_e32 v61, 0xbfb8aa3b, v61
	v_exp_f32_e32 v65, v61
	v_add_u32_e32 v124, 0x220, v126
	v_add_u32_e32 v61, v124, v92
	ds_write_b16_d16_hi v61, v62
	v_mul_f32_e32 v62, v65, v63
	v_bfe_u32 v63, v62, 16, 1
	v_add_u32_e32 v120, 0x330, v126
	v_add3_u32 v63, v62, v63, s97
	v_add_u32_e32 v62, v120, v92
	ds_write_b16_d16_hi v62, v63
	v_sad_u32 v63, v122, v129, 0
	v_cvt_f32_u32_e32 v63, v63
	v_cmp_lt_i32_e32 vcc, v122, v129
	s_nop 1
	v_cndmask_b32_e32 v65, v99, v103, vcc
	v_mul_f32_e32 v63, v65, v63
	v_mul_f32_e32 v63, 0xbfb8aa3b, v63
	v_exp_f32_e32 v63, v63
	v_bfe_u32 v65, v56, 16, 1
	v_add3_u32 v56, v56, v65, s97
	ds_write_b16_d16_hi v60, v56 offset:32
	v_mul_f32_e32 v56, v63, v57
	v_cvt_pk_bf16_f32 v56, v56, v56
	v_sad_u32 v57, v121, v129, 0
	v_cvt_f32_u32_e32 v57, v57
	v_cmp_lt_i32_e32 vcc, v121, v129
	ds_write_b16_d16_hi v64, v56 offset:32
	s_nop 0
	v_cndmask_b32_e32 v56, v99, v103, vcc
	v_mul_f32_e32 v56, v56, v57
	v_sub_u32_e32 v57, v118, v129
	v_mul_f32_e32 v56, 0xbfb8aa3b, v56
	v_sub_u32_e32 v63, 0, v57
	v_exp_f32_e32 v56, v56
	v_max_i32_e32 v57, v57, v63
	v_cvt_f32_u32_e32 v57, v57
	v_cmp_lt_i32_e32 vcc, v118, v129
	v_mul_f32_e32 v56, v56, v58
	s_nop 0
	v_cndmask_b32_e32 v58, v99, v103, vcc
	v_mul_f32_e32 v57, v58, v57
	v_mul_f32_e32 v57, 0xbfb8aa3b, v57
	v_exp_f32_e32 v57, v57
	v_cvt_pk_bf16_f32 v56, v56, v56
	ds_write_b16_d16_hi v61, v56 offset:32
	v_mul_f32_e32 v56, v57, v59
	v_cvt_pk_bf16_f32 v56, v56, v56
	v_sad_u32 v57, v123, v128, 0
	v_cvt_f32_u32_e32 v57, v57
	v_cmp_lt_i32_e32 vcc, v123, v128
	ds_write_b16_d16_hi v62, v56 offset:32
	s_nop 0
	v_cndmask_b32_e32 v56, v99, v103, vcc
	v_mul_f32_e32 v56, v56, v57
	v_sub_u32_e32 v57, v122, v128
	v_mul_f32_e32 v56, 0xbfb8aa3b, v56
	v_sub_u32_e32 v58, 0, v57
	v_exp_f32_e32 v56, v56
	v_max_i32_e32 v57, v57, v58
	v_cvt_f32_u32_e32 v57, v57
	v_cmp_lt_i32_e32 vcc, v122, v128
	v_mul_f32_e32 v52, v56, v52
	s_nop 0
	v_cndmask_b32_e32 v56, v99, v103, vcc
	v_mul_f32_e32 v56, v56, v57
	v_mul_f32_e32 v56, 0xbfb8aa3b, v56
	v_exp_f32_e32 v56, v56
	v_bfe_u32 v57, v52, 16, 1
	v_add3_u32 v52, v52, v57, s97
	ds_write_b16_d16_hi v60, v52 offset:64
	v_mul_f32_e32 v52, v56, v53
	v_cvt_pk_bf16_f32 v52, v52, v52
	v_sad_u32 v53, v121, v128, 0
	v_cvt_f32_u32_e32 v53, v53
	v_cmp_lt_i32_e32 vcc, v121, v128
	ds_write_b16_d16_hi v64, v52 offset:64
	s_nop 0
	v_cndmask_b32_e32 v52, v99, v103, vcc
	v_mul_f32_e32 v52, v52, v53
	v_sub_u32_e32 v53, v118, v128
	v_mul_f32_e32 v52, 0xbfb8aa3b, v52
	v_sub_u32_e32 v56, 0, v53
	v_exp_f32_e32 v52, v52
	v_max_i32_e32 v53, v53, v56
	v_cvt_f32_u32_e32 v53, v53
	v_cmp_lt_i32_e32 vcc, v118, v128
	v_mul_f32_e32 v52, v52, v54
	s_nop 0
	v_cndmask_b32_e32 v54, v99, v103, vcc
	v_mul_f32_e32 v53, v54, v53
	v_mul_f32_e32 v53, 0xbfb8aa3b, v53
	v_exp_f32_e32 v53, v53
	v_cvt_pk_bf16_f32 v52, v52, v52
	ds_write_b16_d16_hi v61, v52 offset:64
	v_mul_f32_e32 v52, v53, v55
	v_cvt_pk_bf16_f32 v52, v52, v52
	v_sad_u32 v53, v123, v127, 0
	v_cvt_f32_u32_e32 v53, v53
	v_cmp_lt_i32_e32 vcc, v123, v127
	ds_write_b16_d16_hi v62, v52 offset:64
	s_nop 0
	v_cndmask_b32_e32 v52, v99, v103, vcc
	v_mul_f32_e32 v52, v52, v53
	v_sad_u32 v53, v122, v127, 0
	v_mul_f32_e32 v52, 0xbfb8aa3b, v52
	v_exp_f32_e32 v52, v52
	v_cvt_f32_u32_e32 v53, v53
	v_cmp_lt_i32_e32 vcc, v122, v127
	v_mul_f32_e32 v48, v52, v48
	s_nop 0
	v_cndmask_b32_e32 v52, v99, v103, vcc
	v_mul_f32_e32 v52, v52, v53
	v_mul_f32_e32 v52, 0xbfb8aa3b, v52
	v_exp_f32_e32 v52, v52
	v_cvt_pk_bf16_f32 v48, v48, v48
	ds_write_b16_d16_hi v60, v48 offset:96
	v_mul_f32_e32 v48, v52, v49
	v_cvt_pk_bf16_f32 v48, v48, v48
	v_sad_u32 v49, v121, v127, 0
	v_cvt_f32_u32_e32 v49, v49
	v_cmp_lt_i32_e32 vcc, v121, v127
	ds_write_b16_d16_hi v64, v48 offset:96
	s_nop 0
	v_cndmask_b32_e32 v48, v99, v103, vcc
	v_mul_f32_e32 v48, v48, v49
	v_sad_u32 v49, v118, v127, 0
	v_mul_f32_e32 v48, 0xbfb8aa3b, v48
	v_exp_f32_e32 v48, v48
	v_cvt_f32_u32_e32 v49, v49
	v_cmp_lt_i32_e32 vcc, v118, v127
	v_mul_f32_e32 v48, v48, v50
	s_nop 0
	v_cndmask_b32_e32 v50, v99, v103, vcc
	v_mul_f32_e32 v49, v50, v49
	v_mul_f32_e32 v49, 0xbfb8aa3b, v49
	v_exp_f32_e32 v49, v49
	v_cvt_pk_bf16_f32 v48, v48, v48
	ds_write_b16_d16_hi v61, v48 offset:96
	v_mul_f32_e32 v48, v49, v51
	v_cvt_pk_bf16_f32 v48, v48, v48
	v_sad_u32 v49, v123, v116, 0
	v_cvt_f32_u32_e32 v49, v49
	v_cmp_lt_i32_e32 vcc, v123, v116
	ds_write_b16_d16_hi v62, v48 offset:96
	s_nop 0
	v_cndmask_b32_e32 v48, v99, v103, vcc
	v_mul_f32_e32 v48, v48, v49
	v_sad_u32 v49, v122, v116, 0
	v_mul_f32_e32 v48, 0xbfb8aa3b, v48
	v_exp_f32_e32 v48, v48
	v_cvt_f32_u32_e32 v49, v49
	v_cmp_lt_i32_e32 vcc, v122, v116
	v_mul_f32_e32 v44, v48, v44
	s_nop 0
	v_cndmask_b32_e32 v48, v99, v103, vcc
	v_mul_f32_e32 v48, v48, v49
	v_mul_f32_e32 v48, 0xbfb8aa3b, v48
	v_exp_f32_e32 v48, v48
	v_cvt_pk_bf16_f32 v44, v44, v44
	ds_write_b16_d16_hi v60, v44 offset:128
	v_mul_f32_e32 v44, v48, v45
	v_cvt_pk_bf16_f32 v44, v44, v44
	v_sad_u32 v45, v121, v116, 0
	v_cvt_f32_u32_e32 v45, v45
	v_cmp_lt_i32_e32 vcc, v121, v116
	ds_write_b16_d16_hi v64, v44 offset:128
	s_nop 0
	v_cndmask_b32_e32 v44, v99, v103, vcc
	v_mul_f32_e32 v44, v44, v45
	v_sad_u32 v45, v118, v116, 0
	v_mul_f32_e32 v44, 0xbfb8aa3b, v44
	v_exp_f32_e32 v44, v44
	v_cvt_f32_u32_e32 v45, v45
	v_cmp_lt_i32_e32 vcc, v118, v116
	v_mul_f32_e32 v44, v44, v46
	s_nop 0
	v_cndmask_b32_e32 v46, v99, v103, vcc
	v_mul_f32_e32 v45, v46, v45
	v_mul_f32_e32 v45, 0xbfb8aa3b, v45
	v_exp_f32_e32 v45, v45
	v_cvt_pk_bf16_f32 v44, v44, v44
	ds_write_b16_d16_hi v61, v44 offset:128
	v_mul_f32_e32 v44, v45, v47
	v_cvt_pk_bf16_f32 v44, v44, v44
	v_sad_u32 v45, v123, v119, 0
	v_cvt_f32_u32_e32 v45, v45
	v_cmp_lt_i32_e32 vcc, v123, v119
	ds_write_b16_d16_hi v62, v44 offset:128
	s_nop 0
	v_cndmask_b32_e32 v44, v99, v103, vcc
	v_mul_f32_e32 v44, v44, v45
	v_sub_u32_e32 v45, v122, v119
	v_mul_f32_e32 v44, 0xbfb8aa3b, v44
	v_sub_u32_e32 v46, 0, v45
	v_exp_f32_e32 v44, v44
	v_max_i32_e32 v45, v45, v46
	v_cvt_f32_u32_e32 v45, v45
	v_cmp_lt_i32_e32 vcc, v122, v119
	v_mul_f32_e32 v40, v44, v40
	s_nop 0
	v_cndmask_b32_e32 v44, v99, v103, vcc
	v_mul_f32_e32 v44, v44, v45
	v_mul_f32_e32 v44, 0xbfb8aa3b, v44
	v_exp_f32_e32 v44, v44
	v_bfe_u32 v45, v40, 16, 1
	v_add3_u32 v40, v40, v45, s97
	ds_write_b16_d16_hi v60, v40 offset:160
	v_mul_f32_e32 v40, v44, v41
	v_cvt_pk_bf16_f32 v40, v40, v40
	v_sad_u32 v41, v121, v119, 0
	v_cvt_f32_u32_e32 v41, v41
	v_cmp_lt_i32_e32 vcc, v121, v119
	ds_write_b16_d16_hi v64, v40 offset:160
	s_nop 0
	v_cndmask_b32_e32 v40, v99, v103, vcc
	v_mul_f32_e32 v40, v40, v41
	v_sub_u32_e32 v41, v118, v119
	v_mul_f32_e32 v40, 0xbfb8aa3b, v40
	v_sub_u32_e32 v44, 0, v41
	v_exp_f32_e32 v40, v40
	v_max_i32_e32 v41, v41, v44
	v_cvt_f32_u32_e32 v41, v41
	v_cmp_lt_i32_e32 vcc, v118, v119
	v_mul_f32_e32 v40, v40, v42
	s_nop 0
	v_cndmask_b32_e32 v42, v99, v103, vcc
	v_mul_f32_e32 v41, v42, v41
	v_mul_f32_e32 v41, 0xbfb8aa3b, v41
	v_exp_f32_e32 v41, v41
	v_cvt_pk_bf16_f32 v40, v40, v40
	ds_write_b16_d16_hi v61, v40 offset:160
	v_mul_f32_e32 v40, v41, v43
	v_cvt_pk_bf16_f32 v40, v40, v40
	v_sad_u32 v41, v123, v117, 0
	v_cvt_f32_u32_e32 v41, v41
	v_cmp_lt_i32_e32 vcc, v123, v117
	ds_write_b16_d16_hi v62, v40 offset:160
	s_nop 0
	v_cndmask_b32_e32 v40, v99, v103, vcc
	v_mul_f32_e32 v40, v40, v41
	v_sad_u32 v41, v122, v117, 0
	v_mul_f32_e32 v40, 0xbfb8aa3b, v40
	v_exp_f32_e32 v40, v40
	v_cvt_f32_u32_e32 v41, v41
	v_cmp_lt_i32_e32 vcc, v122, v117
	v_mul_f32_e32 v36, v40, v36
	s_nop 0
	v_cndmask_b32_e32 v40, v99, v103, vcc
	v_mul_f32_e32 v40, v40, v41
	v_mul_f32_e32 v40, 0xbfb8aa3b, v40
	v_exp_f32_e32 v40, v40
	v_cvt_pk_bf16_f32 v36, v36, v36
	ds_write_b16_d16_hi v60, v36 offset:192
	v_mul_f32_e32 v36, v40, v37
	v_cvt_pk_bf16_f32 v36, v36, v36
	v_sad_u32 v37, v121, v117, 0
	v_cvt_f32_u32_e32 v37, v37
	v_cmp_lt_i32_e32 vcc, v121, v117
	ds_write_b16_d16_hi v64, v36 offset:192
	s_nop 0
	v_cndmask_b32_e32 v36, v99, v103, vcc
	v_mul_f32_e32 v36, v36, v37
	v_sad_u32 v37, v118, v117, 0
	v_mul_f32_e32 v36, 0xbfb8aa3b, v36
	v_exp_f32_e32 v36, v36
	v_cvt_f32_u32_e32 v37, v37
	v_cmp_lt_i32_e32 vcc, v118, v117
	v_mul_f32_e32 v36, v36, v38
	v_mad_u64_u32 v[116:117], s[22:23], v105, s4, v[98:99]
	v_cndmask_b32_e32 v38, v99, v103, vcc
	v_mul_f32_e32 v37, v38, v37
	v_mul_f32_e32 v37, 0xbfb8aa3b, v37
	v_exp_f32_e32 v37, v37
	v_cvt_pk_bf16_f32 v36, v36, v36
	ds_write_b16_d16_hi v61, v36 offset:192
	v_mul_f32_e32 v36, v37, v39
	v_cvt_pk_bf16_f32 v36, v36, v36
	v_sad_u32 v37, v123, v115, 0
	v_cvt_f32_u32_e32 v37, v37
	v_cmp_lt_i32_e32 vcc, v123, v115
	ds_write_b16_d16_hi v62, v36 offset:192
	s_nop 0
	v_cndmask_b32_e32 v36, v99, v103, vcc
	v_mul_f32_e32 v36, v36, v37
	v_sub_u32_e32 v37, v122, v115
	v_mul_f32_e32 v36, 0xbfb8aa3b, v36
	v_sub_u32_e32 v38, 0, v37
	v_exp_f32_e32 v36, v36
	v_max_i32_e32 v37, v37, v38
	v_cvt_f32_u32_e32 v37, v37
	v_cmp_lt_i32_e32 vcc, v122, v115
	v_mul_f32_e32 v32, v36, v32
	s_nop 0
	v_cndmask_b32_e32 v36, v99, v103, vcc
	v_mul_f32_e32 v36, v36, v37
	v_mul_f32_e32 v36, 0xbfb8aa3b, v36
	v_exp_f32_e32 v36, v36
	v_bfe_u32 v37, v32, 16, 1
	v_add3_u32 v32, v32, v37, s97
	ds_write_b16_d16_hi v60, v32 offset:224
	v_mul_f32_e32 v32, v36, v33
	v_cvt_pk_bf16_f32 v32, v32, v32
	v_sad_u32 v33, v121, v115, 0
	v_cvt_f32_u32_e32 v33, v33
	v_cmp_lt_i32_e32 vcc, v121, v115
	ds_write_b16_d16_hi v64, v32 offset:224
	s_nop 0
	v_cndmask_b32_e32 v32, v99, v103, vcc
	v_mul_f32_e32 v32, v32, v33
	v_sub_u32_e32 v33, v118, v115
	v_mul_f32_e32 v32, 0xbfb8aa3b, v32
	v_sub_u32_e32 v36, 0, v33
	v_exp_f32_e32 v32, v32
	v_max_i32_e32 v33, v33, v36
	v_cvt_f32_u32_e32 v33, v33
	v_cmp_lt_i32_e32 vcc, v118, v115
	v_mul_f32_e32 v32, v32, v34
	s_nop 0
	v_cndmask_b32_e32 v34, v99, v103, vcc
	v_mul_f32_e32 v33, v34, v33
	v_mul_f32_e32 v33, 0xbfb8aa3b, v33
	v_exp_f32_e32 v33, v33
	v_cvt_pk_bf16_f32 v32, v32, v32
	ds_write_b16_d16_hi v61, v32 offset:224
	v_mul_f32_e32 v32, v33, v35
	v_cvt_pk_bf16_f32 v32, v32, v32
	ds_write_b16_d16_hi v62, v32 offset:224
	s_waitcnt lgkmcnt(0)
	s_barrier
	ds_read_b128 v[32:35], v107 offset:54272
	ds_read_b128 v[48:51], v107 offset:54336
	ds_read_b128 v[40:43], v107 offset:63488
	ds_read_b128 v[52:55], v107 offset:63552
	s_waitcnt lgkmcnt(3)
	v_mfma_f32_16x16x32_bf16 v[36:39], v[24:27], v[32:35], 0
	ds_read_b128 v[72:75], v107 offset:56640
	ds_read_b128 v[76:79], v68 offset:63552
	ds_read_b128 v[84:87], v107 offset:58944
	s_waitcnt lgkmcnt(4)
	v_mfma_f32_16x16x32_bf16 v[44:47], v[24:27], v[40:43], 0
	ds_read_b128 v[128:131], v107 offset:61248
	ds_read_b128 v[148:151], v116 offset:64
	ds_read_b128 v[144:147], v116 offset:4352
	v_mfma_f32_16x16x32_bf16 v[32:35], v[28:31], v[32:35], 0
	ds_read_b128 v[164:167], v116 offset:4544
	v_cmp_lt_i32_e32 vcc, v235, v229
	v_mfma_f32_16x16x32_bf16 v[40:43], v[28:31], v[40:43], 0
	v_mfma_f32_16x16x32_bf16 v[56:59], v[20:23], v[48:51], v[36:39]
	v_mfma_f32_16x16x32_bf16 v[36:39], v[16:19], v[48:51], v[32:35]
	ds_read_b128 v[48:51], v68 offset:63488
	s_waitcnt lgkmcnt(8)
	v_mfma_f32_16x16x32_bf16 v[32:35], v[16:19], v[52:55], v[40:43]
	s_nop 2
	ds_read_b128 v[40:43], v107 offset:56576
	v_mfma_f32_16x16x32_bf16 v[60:63], v[20:23], v[52:55], v[44:47]
	s_waitcnt lgkmcnt(0)
	v_mfma_f32_16x16x32_bf16 v[44:47], v[24:27], v[40:43], 0
	v_mfma_f32_16x16x32_bf16 v[52:55], v[24:27], v[48:51], 0
	v_mfma_f32_16x16x32_bf16 v[40:43], v[28:31], v[40:43], 0
	v_mfma_f32_16x16x32_bf16 v[48:51], v[28:31], v[48:51], 0
	v_mfma_f32_16x16x32_bf16 v[64:67], v[20:23], v[72:75], v[44:47]
	v_mfma_f32_16x16x32_bf16 v[44:47], v[16:19], v[72:75], v[40:43]
	ds_read_b128 v[72:75], v88 offset:63488
	ds_read_b128 v[88:91], v88 offset:63552
	v_mfma_f32_16x16x32_bf16 v[40:43], v[16:19], v[76:79], v[48:51]
	s_nop 2
	ds_read_b128 v[48:51], v107 offset:58880
	v_mfma_f32_16x16x32_bf16 v[68:71], v[20:23], v[76:79], v[52:55]
	s_waitcnt lgkmcnt(0)
	v_mfma_f32_16x16x32_bf16 v[52:55], v[24:27], v[48:51], 0
	v_mfma_f32_16x16x32_bf16 v[48:51], v[28:31], v[48:51], 0
	v_mfma_f32_16x16x32_bf16 v[80:83], v[28:31], v[72:75], 0
	v_mfma_f32_16x16x32_bf16 v[76:79], v[24:27], v[72:75], 0
	v_mfma_f32_16x16x32_bf16 v[72:75], v[20:23], v[84:87], v[52:55]
	v_mfma_f32_16x16x32_bf16 v[52:55], v[16:19], v[84:87], v[48:51]
	v_mfma_f32_16x16x32_bf16 v[48:51], v[16:19], v[88:91], v[80:83]
	s_nop 3
	ds_read_b128 v[80:83], v107 offset:61184
	v_mfma_f32_16x16x32_bf16 v[76:79], v[20:23], v[88:91], v[76:79]
	ds_read_b128 v[88:91], v110 offset:63488
	s_waitcnt lgkmcnt(1)
	v_mfma_f32_16x16x32_bf16 v[84:87], v[24:27], v[80:83], 0
	s_waitcnt lgkmcnt(0)
	v_mfma_f32_16x16x32_bf16 v[92:95], v[24:27], v[88:91], 0
	v_mfma_f32_16x16x32_bf16 v[24:27], v[20:23], v[128:131], v[84:87]
	s_nop 4
	ds_read_b128 v[84:87], v110 offset:63552
	v_mfma_f32_16x16x32_bf16 v[80:83], v[28:31], v[80:83], 0
	v_mfma_f32_16x16x32_bf16 v[88:91], v[28:31], v[88:91], 0
	s_waitcnt lgkmcnt(0)
	v_mfma_f32_16x16x32_bf16 v[28:31], v[20:23], v[84:87], v[92:95]
	v_mfma_f32_16x16x32_bf16 v[20:23], v[16:19], v[128:131], v[80:83]
	s_nop 3
	ds_read_b128 v[80:83], v116
	v_mfma_f32_16x16x32_bf16 v[16:19], v[16:19], v[84:87], v[88:91]
	v_mul_u32_u24_e32 v84, 0x88, v101
	v_lshl_add_u32 v98, v84, 1, v98
	ds_read_b128 v[84:87], v98 offset:36864
	ds_read_b128 v[92:95], v98 offset:41216
	ds_read_b128 v[132:135], v98 offset:45568
	ds_read_b128 v[156:159], v98 offset:45632
	ds_read_b128 v[140:143], v98 offset:49920
	ds_read_b128 v[160:163], v98 offset:49984
	s_waitcnt lgkmcnt(5)
	v_mfma_f32_16x16x32_bf16 v[88:91], v[80:83], v[84:87], 0
	ds_read_b128 v[152:155], v98 offset:41280
	s_waitcnt lgkmcnt(5)
	v_mfma_f32_16x16x32_bf16 v[128:131], v[80:83], v[92:95], 0
	s_waitcnt lgkmcnt(4)
	v_mfma_f32_16x16x32_bf16 v[136:139], v[80:83], v[132:135], 0
	s_waitcnt lgkmcnt(2)
	v_mfma_f32_16x16x32_bf16 v[80:83], v[80:83], v[140:143], 0
	v_mfma_f32_16x16x32_bf16 v[84:87], v[144:147], v[84:87], 0
	v_mfma_f32_16x16x32_bf16 v[92:95], v[144:147], v[92:95], 0
	v_mfma_f32_16x16x32_bf16 v[132:135], v[144:147], v[132:135], 0
	v_mfma_f32_16x16x32_bf16 v[140:143], v[144:147], v[140:143], 0
	ds_read_b128 v[144:147], v98 offset:36928
	s_waitcnt lgkmcnt(0)
	v_mfma_f32_16x16x32_bf16 v[88:91], v[148:151], v[144:147], v[88:91]
	v_mfma_f32_16x16x32_bf16 v[128:131], v[148:151], v[152:155], v[128:131]
	v_mfma_f32_16x16x32_bf16 v[136:139], v[148:151], v[156:159], v[136:139]
	v_mfma_f32_16x16x32_bf16 v[80:83], v[148:151], v[160:163], v[80:83]
	ds_read_b128 v[148:151], v116 offset:4416
	s_waitcnt lgkmcnt(0)
	v_mfma_f32_16x16x32_bf16 v[84:87], v[148:151], v[144:147], v[84:87]
	ds_read_b128 v[144:147], v116 offset:128
	v_mfma_f32_16x16x32_bf16 v[92:95], v[148:151], v[152:155], v[92:95]
	ds_read_b128 v[152:155], v98 offset:41344
	v_mfma_f32_16x16x32_bf16 v[132:135], v[148:151], v[156:159], v[132:135]
	ds_read_b128 v[156:159], v98 offset:45696
	v_mfma_f32_16x16x32_bf16 v[140:143], v[148:151], v[160:163], v[140:143]
	ds_read_b128 v[148:151], v98 offset:36992
	ds_read_b128 v[160:163], v98 offset:50048
	s_waitcnt lgkmcnt(1)
	v_mfma_f32_16x16x32_bf16 v[88:91], v[144:147], v[148:151], v[88:91]
	v_mfma_f32_16x16x32_bf16 v[128:131], v[144:147], v[152:155], v[128:131]
	v_mfma_f32_16x16x32_bf16 v[136:139], v[144:147], v[156:159], v[136:139]
	s_waitcnt lgkmcnt(0)
	v_mfma_f32_16x16x32_bf16 v[80:83], v[144:147], v[160:163], v[80:83]
	ds_read_b128 v[144:147], v116 offset:4480
	s_waitcnt lgkmcnt(0)
	v_mfma_f32_16x16x32_bf16 v[84:87], v[144:147], v[148:151], v[84:87]
	ds_read_b128 v[148:151], v116 offset:192
	v_mfma_f32_16x16x32_bf16 v[92:95], v[144:147], v[152:155], v[92:95]
	v_mfma_f32_16x16x32_bf16 v[132:135], v[144:147], v[156:159], v[132:135]
	ds_read_b128 v[156:159], v98 offset:45760
	v_mfma_f32_16x16x32_bf16 v[140:143], v[144:147], v[160:163], v[140:143]
	ds_read_b128 v[144:147], v98 offset:37056
	ds_read_b128 v[160:163], v98 offset:50112
	s_waitcnt lgkmcnt(1)
	v_mfma_f32_16x16x32_bf16 v[152:155], v[148:151], v[144:147], v[88:91]
	s_nop 2
	ds_read_b128 v[88:91], v98 offset:41408
	s_waitcnt lgkmcnt(0)
	v_mfma_f32_16x16x32_bf16 v[128:131], v[148:151], v[88:91], v[128:131]
	v_mfma_f32_16x16x32_bf16 v[88:91], v[164:167], v[88:91], v[92:95]
	s_nop 2
	v_cvt_f32_i32_e32 v92, v109
	v_sub_u32_e32 v93, 0x80, v100
	v_cvt_f32_i32_e32 v93, v93
	v_mfma_f32_16x16x32_bf16 v[136:139], v[148:151], v[156:159], v[136:139]
	v_mul_f32_e32 v92, v92, v99
	v_mul_f32_e32 v92, 0xbfb8aa3b, v92
	v_exp_f32_e32 v98, v92
	v_mul_f32_e32 v92, v93, v103
	v_mul_f32_e32 v92, 0xbfb8aa3b, v92
	v_exp_f32_e32 v105, v92
	v_fma_f32 v56, v98, v56, v152
	v_fma_f32 v64, v98, v64, v128
	v_mfma_f32_16x16x32_bf16 v[148:151], v[148:151], v[160:163], v[80:83]
	v_fmac_f32_e32 v56, v105, v60
	v_lshlrev_b32_e32 v60, 2, v101
	v_add_u32_e32 v101, v113, v60
	v_fmac_f32_e32 v64, v105, v68
	ds_write2_b32 v101, v56, v64 offset1:16
	v_cvt_f32_i32_e32 v64, v108
	v_sub_u32_e32 v68, 0x80, v109
	v_cvt_f32_i32_e32 v68, v68
	v_fma_f32 v56, v98, v72, v136
	v_mul_f32_e32 v64, v64, v99
	v_mul_f32_e32 v64, 0xbfb8aa3b, v64
	v_mul_f32_e32 v68, v68, v103
	v_exp_f32_e32 v64, v64
	v_mul_f32_e32 v68, 0xbfb8aa3b, v68
	v_exp_f32_e32 v68, v68
	v_fma_f32 v24, v98, v24, v148
	v_fmac_f32_e32 v56, v105, v76
	v_fmac_f32_e32 v24, v105, v28
	ds_write2_b32 v101, v56, v24 offset0:32 offset1:48
	v_fma_f32 v24, v64, v57, v153
	v_fma_f32 v56, v64, v65, v129
	v_fmac_f32_e32 v24, v68, v61
	v_add_u32_e32 v28, v114, v60
	v_fmac_f32_e32 v56, v68, v69
	ds_write2_b32 v28, v24, v56 offset1:16
	v_cvt_f32_i32_e32 v56, v106
	v_sub_u32_e32 v57, 0x80, v108
	v_cvt_f32_i32_e32 v57, v57
	v_fma_f32 v24, v64, v73, v137
	v_mul_f32_e32 v56, v56, v99
	v_mul_f32_e32 v56, 0xbfb8aa3b, v56
	v_mul_f32_e32 v57, v57, v103
	v_exp_f32_e32 v56, v56
	v_mul_f32_e32 v57, 0xbfb8aa3b, v57
	v_exp_f32_e32 v57, v57
	v_fma_f32 v25, v64, v25, v149
	v_fmac_f32_e32 v24, v68, v77
	v_fmac_f32_e32 v25, v68, v29
	ds_write2_b32 v28, v24, v25 offset0:32 offset1:48
	v_fma_f32 v24, v56, v58, v154
	v_fma_f32 v28, v56, v66, v130
	v_fmac_f32_e32 v24, v57, v62
	v_add_u32_e32 v25, v112, v60
	v_fmac_f32_e32 v28, v57, v70
	ds_write2_b32 v25, v24, v28 offset1:16
	v_add_u32_e32 v28, 4, v100
	v_fma_f32 v24, v56, v74, v138
	v_cvt_f32_i32_e32 v28, v28
	v_fma_f32 v26, v56, v26, v150
	v_sub_u32_e32 v29, 0x80, v106
	v_fmac_f32_e32 v24, v57, v78
	v_cvt_f32_i32_e32 v29, v29
	v_fmac_f32_e32 v26, v57, v30
	ds_write2_b32 v25, v24, v26 offset0:32 offset1:48
	v_cvt_f32_i32_e32 v25, v122
	v_sub_u32_e32 v26, 0x80, v123
	v_cvt_f32_i32_e32 v26, v26
	v_mul_f32_e32 v28, v28, v99
	v_mul_f32_e32 v28, 0xbfb8aa3b, v28
	v_mul_f32_e32 v29, v29, v103
	v_exp_f32_e32 v28, v28
	v_mul_f32_e32 v29, 0xbfb8aa3b, v29
	v_mul_f32_e32 v25, v25, v99
	v_exp_f32_e32 v29, v29
	v_mul_f32_e32 v25, 0xbfb8aa3b, v25
	v_mul_f32_e32 v26, v26, v103
	v_mfma_f32_16x16x32_bf16 v[84:87], v[164:167], v[144:147], v[84:87]
	v_exp_f32_e32 v25, v25
	v_mul_f32_e32 v26, 0xbfb8aa3b, v26
	v_exp_f32_e32 v26, v26
	v_mfma_f32_16x16x32_bf16 v[80:83], v[164:167], v[156:159], v[132:135]
	v_fmac_f32_e32 v155, v28, v59
	v_fmac_f32_e32 v131, v28, v67
	v_fmac_f32_e32 v139, v28, v75
	v_mfma_f32_16x16x32_bf16 v[92:95], v[164:167], v[160:163], v[140:143]
	v_fmac_f32_e32 v151, v28, v27
	v_fmac_f32_e32 v155, v29, v63
	v_add_u32_e32 v24, v111, v60
	v_fmac_f32_e32 v131, v29, v71
	v_fmac_f32_e32 v139, v29, v79
	v_fmac_f32_e32 v151, v29, v31
	ds_write2_b32 v24, v155, v131 offset1:16
	ds_write2_b32 v24, v139, v151 offset0:32 offset1:48
	v_fma_f32 v24, v25, v36, v84
	v_fma_f32 v28, v25, v44, v88
	v_fmac_f32_e32 v24, v26, v32
	v_add_u32_e32 v27, v126, v60
	v_fmac_f32_e32 v28, v26, v40
	ds_write2_b32 v27, v24, v28 offset1:16
	v_fma_f32 v24, v25, v52, v80
	v_cvt_f32_i32_e32 v28, v121
	v_fma_f32 v20, v25, v20, v92
	v_sub_u32_e32 v25, 0x80, v122
	v_cvt_f32_i32_e32 v25, v25
	v_mul_f32_e32 v28, v28, v99
	v_mul_f32_e32 v28, 0xbfb8aa3b, v28
	v_exp_f32_e32 v28, v28
	v_mul_f32_e32 v25, v25, v103
	v_mul_f32_e32 v25, 0xbfb8aa3b, v25
	v_exp_f32_e32 v25, v25
	v_fmac_f32_e32 v24, v26, v48
	v_fmac_f32_e32 v20, v26, v16
	ds_write2_b32 v27, v24, v20 offset0:32 offset1:48
	v_fma_f32 v16, v28, v37, v85
	v_fma_f32 v24, v28, v45, v89
	v_fmac_f32_e32 v16, v25, v33
	v_add_u32_e32 v20, v125, v60
	v_fmac_f32_e32 v24, v25, v41
	ds_write2_b32 v20, v16, v24 offset1:16
	v_cvt_f32_i32_e32 v24, v118
	v_sub_u32_e32 v26, 0x80, v121
	v_cvt_f32_i32_e32 v26, v26
	v_fma_f32 v16, v28, v53, v81
	v_mul_f32_e32 v24, v24, v99
	v_mul_f32_e32 v24, 0xbfb8aa3b, v24
	v_mul_f32_e32 v26, v26, v103
	v_exp_f32_e32 v24, v24
	v_mul_f32_e32 v26, 0xbfb8aa3b, v26
	v_exp_f32_e32 v26, v26
	v_fma_f32 v21, v28, v21, v93
	v_fmac_f32_e32 v16, v25, v49
	v_fmac_f32_e32 v21, v25, v17
	ds_write2_b32 v20, v16, v21 offset0:32 offset1:48
	v_fma_f32 v16, v24, v38, v86
	v_fma_f32 v20, v24, v46, v90
	v_fmac_f32_e32 v16, v26, v34
	v_add_u32_e32 v17, v124, v60
	v_fmac_f32_e32 v20, v26, v42
	ds_write2_b32 v17, v16, v20 offset1:16
	v_add_u32_e32 v20, 20, v100
	v_cvt_f32_i32_e32 v20, v20
	v_fma_f32 v21, v24, v22, v94
	v_sub_u32_e32 v22, 0x80, v118
	v_cvt_f32_i32_e32 v22, v22
	v_mul_f32_e32 v20, v20, v99
	v_mul_f32_e32 v20, 0xbfb8aa3b, v20
	v_exp_f32_e32 v20, v20
	v_mul_f32_e32 v22, v22, v103
	v_mul_f32_e32 v22, 0xbfb8aa3b, v22
	v_exp_f32_e32 v22, v22
	v_fma_f32 v16, v24, v54, v82
	v_fmac_f32_e32 v16, v26, v50
	v_fmac_f32_e32 v21, v26, v18
	v_fmac_f32_e32 v87, v20, v39
	v_fmac_f32_e32 v91, v20, v47
	v_fmac_f32_e32 v83, v20, v55
	v_fmac_f32_e32 v95, v20, v23
	ds_write2_b32 v17, v16, v21 offset0:32 offset1:48
	v_fmac_f32_e32 v87, v22, v35
	v_add_u32_e32 v16, v120, v60
	v_fmac_f32_e32 v91, v22, v43
	v_fmac_f32_e32 v83, v22, v51
	v_fmac_f32_e32 v95, v22, v19
	ds_write2_b32 v16, v87, v91 offset1:16
	ds_write2_b32 v16, v83, v95 offset0:32 offset1:48
	v_mul_lo_u32 v16, v102, s4
	v_lshlrev_b32_e32 v17, 2, v104
	v_add3_u32 v44, s2, v16, v17
	s_waitcnt lgkmcnt(0)
	s_barrier
	ds_read_b128 v[36:39], v44
	ds_read_b128 v[32:35], v44 offset:16
	ds_read_b128 v[28:31], v44 offset:32
	ds_read_b128 v[24:27], v44 offset:48
	ds_read_b128 v[20:23], v44 offset:64
	ds_read_b128 v[16:19], v44 offset:80
	s_waitcnt lgkmcnt(5)
	v_add_f32_e32 v40, 0, v36
	v_add_f32_e32 v40, v40, v37
	v_add_f32_e32 v40, v40, v38
	v_add_f32_e32 v40, v40, v39
	s_waitcnt lgkmcnt(4)
	v_add_f32_e32 v40, v40, v32
	v_add_f32_e32 v40, v40, v33
	v_add_f32_e32 v40, v40, v34
	v_add_f32_e32 v40, v40, v35
	s_waitcnt lgkmcnt(3)
	v_add_f32_e32 v40, v40, v28
	v_add_f32_e32 v40, v40, v29
	v_add_f32_e32 v40, v40, v30
	v_add_f32_e32 v40, v40, v31
	s_waitcnt lgkmcnt(2)
	v_add_f32_e32 v40, v40, v24
	v_add_f32_e32 v40, v40, v25
	v_add_f32_e32 v40, v40, v26
	v_add_f32_e32 v40, v40, v27
	s_waitcnt lgkmcnt(1)
	v_add_f32_e32 v40, v40, v20
	v_add_f32_e32 v40, v40, v21
	v_add_f32_e32 v40, v40, v22
	v_add_f32_e32 v40, v40, v23
	s_waitcnt lgkmcnt(0)
	v_add_f32_e32 v40, v40, v16
	v_add_f32_e32 v48, v40, v17
	ds_read_b128 v[40:43], v44 offset:96
	v_cndmask_b32_e32 v45, v228, v235, vcc
	v_add_f32_e32 v48, v48, v18
	v_lshlrev_b32_e32 v49, 2, v45
	ds_read_b128 v[44:47], v44 offset:112
	v_add_f32_e32 v48, v48, v19
	s_waitcnt lgkmcnt(1)
	v_add_f32_e32 v48, v48, v40
	v_add_f32_e32 v48, v48, v41
	v_add_f32_e32 v48, v48, v42
	v_add_f32_e32 v48, v48, v43
	s_waitcnt lgkmcnt(0)
	v_add_f32_e32 v48, v48, v44
	v_add_f32_e32 v48, v48, v45
	v_add_f32_e32 v48, v48, v46
	v_add_f32_e32 v48, v48, v47
	ds_bpermute_b32 v50, v49, v48
	v_readlane_b32 s4, v254, 0
	v_readlane_b32 s5, v254, 1
	s_waitcnt lgkmcnt(0)
	v_add_f32_e32 v50, v48, v50
	v_fmamk_f32 v52, v50, 0xbc800000, v37
	v_fmamk_f32 v51, v50, 0xbc800000, v36
	v_mul_f32_e32 v53, v52, v52
	v_fmac_f32_e32 v53, v51, v51
	v_fmamk_f32 v38, v50, 0xbc800000, v38
	v_fmac_f32_e32 v53, v38, v38
	v_fmac_f32_e32 v39, 0xbc800000, v50
	v_fmac_f32_e32 v53, v39, v39
	v_fmamk_f32 v54, v50, 0xbc800000, v32
	v_fmac_f32_e32 v53, v54, v54
	v_fmamk_f32 v55, v50, 0xbc800000, v33
	v_fmac_f32_e32 v53, v55, v55
	v_fmamk_f32 v34, v50, 0xbc800000, v34
	v_fmac_f32_e32 v53, v34, v34
	v_fmac_f32_e32 v35, 0xbc800000, v50
	v_fmac_f32_e32 v53, v35, v35
	v_fmamk_f32 v56, v50, 0xbc800000, v28
	v_fmac_f32_e32 v53, v56, v56
	v_fmamk_f32 v57, v50, 0xbc800000, v29
	v_fmac_f32_e32 v53, v57, v57
	v_fmamk_f32 v30, v50, 0xbc800000, v30
	v_fmac_f32_e32 v53, v30, v30
	v_fmac_f32_e32 v31, 0xbc800000, v50
	v_fmac_f32_e32 v53, v31, v31
	v_fmamk_f32 v58, v50, 0xbc800000, v24
	v_fmac_f32_e32 v53, v58, v58
	v_fmamk_f32 v59, v50, 0xbc800000, v25
	v_fmac_f32_e32 v53, v59, v59
	v_fmamk_f32 v26, v50, 0xbc800000, v26
	v_fmac_f32_e32 v53, v26, v26
	v_fmac_f32_e32 v27, 0xbc800000, v50
	v_fmac_f32_e32 v53, v27, v27
	v_fmamk_f32 v60, v50, 0xbc800000, v20
	v_fmac_f32_e32 v53, v60, v60
	v_fmamk_f32 v61, v50, 0xbc800000, v21
	v_fmac_f32_e32 v53, v61, v61
	v_fmamk_f32 v22, v50, 0xbc800000, v22
	v_fmac_f32_e32 v53, v22, v22
	v_fmac_f32_e32 v23, 0xbc800000, v50
	v_mul_f32_e32 v48, 0x3c800000, v50
	v_fmac_f32_e32 v53, v23, v23
	v_fmamk_f32 v62, v50, 0xbc800000, v16
	v_fmac_f32_e32 v53, v62, v62
	v_fmac_f32_e32 v17, 0xbc800000, v50
	v_pk_add_f32 v[36:37], v[18:19], v[48:49] op_sel_hi:[1,0] neg_lo:[0,1] neg_hi:[0,1]
	v_fmac_f32_e32 v53, v17, v17
	v_pk_mul_f32 v[18:19], v[36:37], v[36:37]
	v_pk_add_f32 v[32:33], v[40:41], v[48:49] op_sel_hi:[1,0] neg_lo:[0,1] neg_hi:[0,1]
	v_add_f32_e32 v16, v18, v53
	v_add_f32_e32 v16, v19, v16
	v_pk_mul_f32 v[18:19], v[32:33], v[32:33]
	v_pk_add_f32 v[28:29], v[42:43], v[48:49] op_sel_hi:[1,0] neg_lo:[0,1] neg_hi:[0,1]
	v_add_f32_e32 v16, v18, v16
	v_add_f32_e32 v16, v19, v16
	v_pk_mul_f32 v[18:19], v[28:29], v[28:29]
	v_pk_add_f32 v[24:25], v[44:45], v[48:49] op_sel_hi:[1,0] neg_lo:[0,1] neg_hi:[0,1]
	v_add_f32_e32 v16, v18, v16
	v_add_f32_e32 v16, v19, v16
	v_pk_mul_f32 v[18:19], v[24:25], v[24:25]
	s_waitcnt vmcnt(0)
	v_lshlrev_b32_e32 v40, 16, v12
	v_add_f32_e32 v16, v18, v16
	v_add_f32_e32 v16, v19, v16
	v_pk_add_f32 v[18:19], v[46:47], v[48:49] op_sel_hi:[1,0] neg_lo:[0,1] neg_hi:[0,1]
	v_and_b32_e32 v12, 0xffff0000, v12
	v_pk_mul_f32 v[20:21], v[18:19], v[18:19]
	v_mul_f32_e32 v44, 0xbfb8aa3b, v40
	v_add_f32_e32 v16, v20, v16
	v_add_f32_e32 v16, v21, v16
	ds_bpermute_b32 v20, v49, v16
	v_mul_f32_e32 v45, 0xbfb8aa3b, v12
	v_exp_f32_e32 v44, v44
	v_exp_f32_e32 v45, v45
	v_lshlrev_b32_e32 v41, 16, v13
	s_waitcnt lgkmcnt(0)
	v_add_f32_e32 v16, v16, v20
	v_fmamk_f32 v16, v16, 0x3c800000, v219
	v_cmp_gt_f32_e32 vcc, s36, v16
	v_mul_f32_e32 v20, 0x4b800000, v16
	v_add_f32_e32 v44, 1.0, v44
	v_cndmask_b32_e32 v16, v16, v20, vcc
	v_rsq_f32_e32 v16, v16
	v_add_f32_e32 v45, 1.0, v45
	v_rcp_f32_e32 v44, v44
	v_rcp_f32_e32 v45, v45
	v_mul_f32_e32 v20, 0x45800000, v16
	v_cndmask_b32_e32 v16, v16, v20, vcc
	v_and_b32_e32 v13, 0xffff0000, v13
	v_mul_f32_e32 v40, v44, v40
	v_mul_f32_e32 v44, v52, v16
	v_mul_f32_e32 v12, v45, v12
	v_mul_f32_e32 v45, 0xbfb8aa3b, v41
	v_mul_f32_e32 v12, v12, v44
	v_mul_f32_e32 v44, 0xbfb8aa3b, v13
	v_exp_f32_e32 v45, v45
	v_exp_f32_e32 v44, v44
	v_lshlrev_b32_e32 v42, 16, v14
	v_and_b32_e32 v14, 0xffff0000, v14
	v_add_f32_e32 v45, 1.0, v45
	v_add_f32_e32 v44, 1.0, v44
	v_rcp_f32_e32 v45, v45
	v_rcp_f32_e32 v44, v44
	v_mul_f32_e32 v38, v38, v16
	v_mul_f32_e32 v39, v39, v16
	v_mul_f32_e32 v41, v45, v41
	v_mul_f32_e32 v13, v44, v13
	v_mul_f32_e32 v38, v41, v38
	v_mul_f32_e32 v41, 0xbfb8aa3b, v42
	v_mul_f32_e32 v13, v13, v39
	v_mul_f32_e32 v39, 0xbfb8aa3b, v14
	v_exp_f32_e32 v41, v41
	v_exp_f32_e32 v39, v39
	v_lshlrev_b32_e32 v43, 16, v15
	v_and_b32_e32 v15, 0xffff0000, v15
	v_add_f32_e32 v41, 1.0, v41
	v_add_f32_e32 v39, 1.0, v39
	v_rcp_f32_e32 v41, v41
	v_rcp_f32_e32 v39, v39
	v_lshlrev_b64 v[20:21], 11, v[96:97]
	v_lshl_add_u64 v[20:21], s[52:53], 0, v[20:21]
	v_mul_f32_e32 v41, v41, v42
	v_mul_f32_e32 v42, v55, v16
	v_mul_f32_e32 v14, v39, v14
	v_mul_f32_e32 v14, v14, v42
	v_mul_f32_e32 v42, 0xbfb8aa3b, v15
	v_mul_f32_e32 v39, 0xbfb8aa3b, v43
	v_exp_f32_e32 v42, v42
	v_exp_f32_e32 v39, v39
	v_lshl_add_u64 v[20:21], v[20:21], 0, s[88:89]
	v_mul_f32_e32 v46, v51, v16
	v_add_f32_e32 v42, 1.0, v42
	v_add_f32_e32 v39, 1.0, v39
	v_rcp_f32_e32 v42, v42
	v_rcp_f32_e32 v39, v39
	v_mul_f32_e32 v35, v35, v16
	v_lshl_add_u64 v[20:21], v[20:21], 0, v[184:185]
	v_mul_f32_e32 v15, v42, v15
	v_mul_f32_e32 v40, v40, v46
	v_mul_f32_e32 v44, v54, v16
	v_mul_f32_e32 v34, v34, v16
	v_mul_f32_e32 v39, v39, v43
	v_mul_f32_e32 v15, v15, v35
	v_cvt_pk_bf16_f32 v12, v40, v12
	v_mul_f32_e32 v41, v41, v44
	v_mul_f32_e32 v34, v39, v34
	v_cvt_pk_bf16_f32 v13, v38, v13
	v_cvt_pk_bf16_f32 v14, v41, v14
	v_cvt_pk_bf16_f32 v15, v34, v15
	global_store_dwordx4 v[20:21], v[12:15], off
	v_mul_f32_e32 v30, v30, v16
	v_mul_f32_e32 v26, v26, v16
	v_lshlrev_b32_e32 v12, 16, v8
	v_and_b32_e32 v8, 0xffff0000, v8
	v_mul_f32_e32 v34, 0xbfb8aa3b, v12
	v_mul_f32_e32 v35, 0xbfb8aa3b, v8
	v_exp_f32_e32 v34, v34
	v_exp_f32_e32 v35, v35
	v_lshlrev_b32_e32 v13, 16, v9
	v_and_b32_e32 v9, 0xffff0000, v9
	v_add_f32_e32 v34, 1.0, v34
	v_add_f32_e32 v35, 1.0, v35
	v_rcp_f32_e32 v34, v34
	v_rcp_f32_e32 v35, v35
	v_lshlrev_b32_e32 v14, 16, v10
	v_and_b32_e32 v10, 0xffff0000, v10
	v_mul_f32_e32 v12, v34, v12
	v_mul_f32_e32 v34, v57, v16
	v_mul_f32_e32 v8, v35, v8
	v_mul_f32_e32 v35, 0xbfb8aa3b, v13
	v_exp_f32_e32 v35, v35
	v_mul_f32_e32 v8, v8, v34
	v_mul_f32_e32 v34, 0xbfb8aa3b, v9
	v_exp_f32_e32 v34, v34
	v_add_f32_e32 v35, 1.0, v35
	v_rcp_f32_e32 v35, v35
	v_lshlrev_b32_e32 v15, 16, v11
	v_add_f32_e32 v34, 1.0, v34
	v_rcp_f32_e32 v34, v34
	v_mul_f32_e32 v13, v35, v13
	v_mul_f32_e32 v13, v13, v30
	v_mul_f32_e32 v30, v31, v16
	v_mul_f32_e32 v9, v34, v9
	v_mul_f32_e32 v31, 0xbfb8aa3b, v14
	v_mul_f32_e32 v9, v9, v30
	v_mul_f32_e32 v30, 0xbfb8aa3b, v10
	v_exp_f32_e32 v31, v31
	v_exp_f32_e32 v30, v30
	v_and_b32_e32 v11, 0xffff0000, v11
	v_mul_f32_e32 v38, v56, v16
	v_add_f32_e32 v31, 1.0, v31
	v_add_f32_e32 v30, 1.0, v30
	v_rcp_f32_e32 v31, v31
	v_rcp_f32_e32 v30, v30
	v_mul_f32_e32 v12, v12, v38
	v_mul_f32_e32 v34, v58, v16
	v_mul_f32_e32 v14, v31, v14
	v_mul_f32_e32 v31, v59, v16
	v_mul_f32_e32 v10, v30, v10
	v_mul_f32_e32 v30, 0xbfb8aa3b, v15
	v_exp_f32_e32 v30, v30
	v_mul_f32_e32 v10, v10, v31
	v_mul_f32_e32 v31, 0xbfb8aa3b, v11
	v_exp_f32_e32 v31, v31
	v_add_f32_e32 v30, 1.0, v30
	v_rcp_f32_e32 v30, v30
	v_cvt_pk_bf16_f32 v8, v12, v8
	v_add_f32_e32 v31, 1.0, v31
	v_rcp_f32_e32 v31, v31
	v_mul_f32_e32 v15, v30, v15
	v_mul_f32_e32 v15, v15, v26
	v_mul_f32_e32 v26, v27, v16
	v_mul_f32_e32 v11, v31, v11
	v_mul_f32_e32 v11, v11, v26
	v_mul_f32_e32 v14, v14, v34
	v_cvt_pk_bf16_f32 v9, v13, v9
	v_cvt_pk_bf16_f32 v10, v14, v10
	v_cvt_pk_bf16_f32 v11, v15, v11
	global_store_dwordx4 v[20:21], v[8:11], off offset:16
	v_mul_f32_e32 v14, v60, v16
	s_nop 0
	v_lshlrev_b32_e32 v8, 16, v4
	v_and_b32_e32 v4, 0xffff0000, v4
	v_mul_f32_e32 v12, 0xbfb8aa3b, v8
	v_mul_f32_e32 v13, 0xbfb8aa3b, v4
	v_exp_f32_e32 v12, v12
	v_exp_f32_e32 v13, v13
	v_lshlrev_b32_e32 v9, 16, v5
	v_and_b32_e32 v5, 0xffff0000, v5
	v_add_f32_e32 v12, 1.0, v12
	v_add_f32_e32 v13, 1.0, v13
	v_rcp_f32_e32 v12, v12
	v_rcp_f32_e32 v13, v13
	v_lshlrev_b32_e32 v10, 16, v6
	v_and_b32_e32 v6, 0xffff0000, v6
	v_mul_f32_e32 v8, v12, v8
	v_mul_f32_e32 v12, v61, v16
	v_mul_f32_e32 v4, v13, v4
	v_mul_f32_e32 v13, 0xbfb8aa3b, v9
	v_mul_f32_e32 v4, v4, v12
	v_mul_f32_e32 v12, 0xbfb8aa3b, v5
	v_exp_f32_e32 v13, v13
	v_exp_f32_e32 v12, v12
	v_lshlrev_b32_e32 v11, 16, v7
	v_and_b32_e32 v7, 0xffff0000, v7
	v_add_f32_e32 v13, 1.0, v13
	v_add_f32_e32 v12, 1.0, v12
	v_rcp_f32_e32 v13, v13
	v_rcp_f32_e32 v12, v12
	v_mul_f32_e32 v8, v8, v14
	v_mul_f32_e32 v14, v22, v16
	v_mul_f32_e32 v9, v13, v9
	v_mul_f32_e32 v13, v23, v16
	v_mul_f32_e32 v5, v12, v5
	v_mul_f32_e32 v12, 0xbfb8aa3b, v10
	v_mul_f32_e32 v5, v5, v13
	v_mul_f32_e32 v13, 0xbfb8aa3b, v6
	v_exp_f32_e32 v12, v12
	v_exp_f32_e32 v13, v13
	v_mul_f32_e32 v9, v9, v14
	v_mul_f32_e32 v14, v62, v16
	v_add_f32_e32 v12, 1.0, v12
	v_add_f32_e32 v13, 1.0, v13
	v_rcp_f32_e32 v12, v12
	v_rcp_f32_e32 v13, v13
	v_cvt_pk_bf16_f32 v4, v8, v4
	v_cvt_pk_bf16_f32 v5, v9, v5
	v_mul_f32_e32 v10, v12, v10
	v_mul_f32_e32 v12, v17, v16
	v_mul_f32_e32 v6, v13, v6
	v_mul_f32_e32 v13, 0xbfb8aa3b, v11
	v_mul_f32_e32 v6, v6, v12
	v_mul_f32_e32 v12, 0xbfb8aa3b, v7
	v_exp_f32_e32 v13, v13
	v_exp_f32_e32 v12, v12
	v_mul_f32_e32 v10, v10, v14
	v_mul_f32_e32 v14, v36, v16
	v_add_f32_e32 v13, 1.0, v13
	v_add_f32_e32 v12, 1.0, v12
	v_rcp_f32_e32 v13, v13
	v_rcp_f32_e32 v12, v12
	v_cvt_pk_bf16_f32 v6, v10, v6
	v_mul_f32_e32 v10, v32, v16
	v_mul_f32_e32 v11, v13, v11
	v_mul_f32_e32 v13, v37, v16
	v_mul_f32_e32 v7, v12, v7
	v_mul_f32_e32 v7, v7, v13
	v_mul_f32_e32 v11, v11, v14
	v_cvt_pk_bf16_f32 v7, v11, v7
	global_store_dwordx4 v[20:21], v[4:7], off offset:32
	s_nop 1
	v_lshlrev_b32_e32 v4, 16, v0
	v_and_b32_e32 v0, 0xffff0000, v0
	v_mul_f32_e32 v8, 0xbfb8aa3b, v4
	v_mul_f32_e32 v9, 0xbfb8aa3b, v0
	v_exp_f32_e32 v8, v8
	v_exp_f32_e32 v9, v9
	v_lshlrev_b32_e32 v5, 16, v1
	v_and_b32_e32 v1, 0xffff0000, v1
	v_add_f32_e32 v8, 1.0, v8
	v_add_f32_e32 v9, 1.0, v9
	v_rcp_f32_e32 v8, v8
	v_rcp_f32_e32 v9, v9
	v_lshlrev_b32_e32 v6, 16, v2
	v_and_b32_e32 v2, 0xffff0000, v2
	v_mul_f32_e32 v4, v8, v4
	v_mul_f32_e32 v8, v33, v16
	v_mul_f32_e32 v0, v9, v0
	v_mul_f32_e32 v9, 0xbfb8aa3b, v5
	v_mul_f32_e32 v0, v0, v8
	v_mul_f32_e32 v8, 0xbfb8aa3b, v1
	v_exp_f32_e32 v9, v9
	v_exp_f32_e32 v8, v8
	v_lshlrev_b32_e32 v7, 16, v3
	v_and_b32_e32 v3, 0xffff0000, v3
	v_add_f32_e32 v9, 1.0, v9
	v_add_f32_e32 v8, 1.0, v8
	v_rcp_f32_e32 v9, v9
	v_rcp_f32_e32 v8, v8
	v_mul_f32_e32 v4, v4, v10
	v_mul_f32_e32 v10, v28, v16
	v_mul_f32_e32 v5, v9, v5
	v_mul_f32_e32 v9, v29, v16
	v_mul_f32_e32 v1, v8, v1
	v_mul_f32_e32 v8, 0xbfb8aa3b, v6
	v_mul_f32_e32 v1, v1, v9
	v_mul_f32_e32 v9, 0xbfb8aa3b, v2
	v_exp_f32_e32 v8, v8
	v_exp_f32_e32 v9, v9
	v_mul_f32_e32 v5, v5, v10
	v_mul_f32_e32 v10, v24, v16
	v_add_f32_e32 v8, 1.0, v8
	v_add_f32_e32 v9, 1.0, v9
	v_rcp_f32_e32 v8, v8
	v_rcp_f32_e32 v9, v9
	v_cvt_pk_bf16_f32 v0, v4, v0
	v_cvt_pk_bf16_f32 v1, v5, v1
	v_mul_f32_e32 v6, v8, v6
	v_mul_f32_e32 v8, v25, v16
	v_mul_f32_e32 v2, v9, v2
	v_mul_f32_e32 v9, 0xbfb8aa3b, v7
	v_mul_f32_e32 v2, v2, v8
	v_mul_f32_e32 v8, 0xbfb8aa3b, v3
	v_exp_f32_e32 v9, v9
	v_exp_f32_e32 v8, v8
	v_mul_f32_e32 v6, v6, v10
	v_mul_f32_e32 v10, v18, v16
	v_add_f32_e32 v9, 1.0, v9
	v_add_f32_e32 v8, 1.0, v8
	v_rcp_f32_e32 v9, v9
	v_rcp_f32_e32 v8, v8
	v_cvt_pk_bf16_f32 v2, v6, v2
	v_mul_f32_e32 v7, v9, v7
	v_mul_f32_e32 v9, v19, v16
	v_mul_f32_e32 v3, v8, v3
	v_mul_f32_e32 v3, v3, v9
	v_mul_f32_e32 v7, v7, v10
	v_cvt_pk_bf16_f32 v3, v7, v3
	global_store_dwordx4 v[20:21], v[0:3], off offset:48
	s_barrier
	s_load_dword s20, s[4:5], 0x0
	s_waitcnt lgkmcnt(0)
	s_lshl_b32 s20, s20, 1
	s_add_i32 s38, s20, s38
	s_cmp_ge_i32 s38, s30
	s_cbranch_scc1 .LBB0_202
